# nt loads also for the LayerNorm row reads (x, out, xb: read once)
# speedup vs baseline: 1.0259x; 1.0040x over previous
; __device__ __forceinline__ float bflo(unsigned w) { return __uint_as_float(w << 16); }
; __device__ __forceinline__ float bfhi(unsigned w) { return __uint_as_float(w & 0xffff0000u); }
; __device__ __forceinline__ void ln_phase(const Params& p, const int layer, const int row_lo, const int row_hi, const int wg_id, const int n_wg) {
;     ...
;     for (int m0 = row_lo + gw; m0 < row_hi; m0 += 2 * NGW) {
;         const int m1r = m0 + NGW; const bool ok1 = m1r < row_hi; const int m1 = ok1 ? m1r : m0;
;         const v2u* ob0 = (const v2u*)(OB + (size_t)m0 * DM) + lane; const v2u* ob1 = (const v2u*)(OB + (size_t)m1 * DM) + lane;
;         f32x4 v0[8], v1[8]; v2u w0[8], w1[8]; float s0 = 0.f, s1 = 0.f;
;         if (layer == 0) {
;             const f32x4* xr0 = (const f32x4*)((m0 < NP) ? p.in[0] + (size_t)m0 * DM : p.in[1] + (size_t)(m0 - NP) * DM) + lane;
;             const f32x4* xr1 = (const f32x4*)((m1 < NP) ? p.in[0] + (size_t)m1 * DM : p.in[1] + (size_t)(m1 - NP) * DM) + lane;
; #pragma unroll
;             for (int j = 0; j < 8; ++j) { v0[j] = xr0[64 * j]; v1[j] = xr1[64 * j]; w0[j] = ob0[64 * j]; w1[j] = ob1[64 * j]; }
;         } else {
;             const v2u* xb0 = (const v2u*)(XB + (size_t)m0 * DM) + lane; const v2u* xb1 = (const v2u*)(XB + (size_t)m1 * DM) + lane;
;             v2u a0[8], a1[8];
; #pragma unroll
;             for (int j = 0; j < 8; ++j) { a0[j] = xb0[64 * j]; a1[j] = xb1[64 * j]; w0[j] = ob0[64 * j]; w1[j] = ob1[64 * j]; }
; #pragma unroll
;             for (int j = 0; j < 8; ++j) { v0[j] = (f32x4){bflo(a0[j].x), bfhi(a0[j].x), bflo(a0[j].y), bfhi(a0[j].y)}; v1[j] = (f32x4){bflo(a1[j].x), bfhi(a1[j].x), bflo(a1[j].y), bfhi(a1[j].y)}; }
;         }
.LBB0_792:
	s_movk_i32 s0, 0x1300
	v_add_u32_e32 v2, 0x500, v66
	v_cmp_gt_i32_e64 s[38:39], s0, v66
	s_mov_b64 s[0:1], -1
	s_and_b64 vcc, exec, s[10:11]
	v_cndmask_b32_e64 v2, v66, v2, s[38:39]
	v_ashrrev_i32_e32 v3, 31, v2
	v_lshlrev_b64 v[104:105], 11, v[2:3]
	s_cbranch_vccz .LBB0_794
	v_add_co_u32_e32 v4, vcc, 0xe6000000, v98
	v_lshl_add_u64 v[2:3], v[104:105], 1, v[70:71]
	s_nop 0
	v_addc_co_u32_e32 v5, vcc, -1, v99, vcc
	v_add_co_u32_e32 v10, vcc, 0xe6000200, v98
	global_load_dwordx2 v[6:7], v[2:3], off nt
	global_load_dwordx2 v[8:9], v[2:3], off offset:512 nt
	global_load_dwordx2 v[12:13], v[2:3], off offset:1024 nt
	v_addc_co_u32_e32 v11, vcc, -1, v99, vcc
	v_add_co_u32_e32 v16, vcc, 0xe6000400, v98
	global_load_dwordx2 v[14:15], v[2:3], off offset:1536 nt
	s_nop 0
	global_load_dwordx2 v[4:5], v[4:5], off nt
	s_nop 0
	global_load_dwordx2 v[10:11], v[10:11], off nt
	v_addc_co_u32_e32 v17, vcc, -1, v99, vcc
	v_add_co_u32_e32 v18, vcc, 0xe6000600, v98
	global_load_dwordx2 v[16:17], v[16:17], off nt
	s_nop 0
	v_addc_co_u32_e32 v19, vcc, -1, v99, vcc
	v_add_co_u32_e32 v20, vcc, 0xe6000800, v98
	global_load_dwordx2 v[18:19], v[18:19], off nt
	s_nop 0
	v_addc_co_u32_e32 v21, vcc, -1, v99, vcc
	v_add_co_u32_e32 v22, vcc, 0xe6000a00, v98
	global_load_dwordx2 v[20:21], v[20:21], off nt
	s_nop 0
	global_load_dwordx2 v[30:31], v[2:3], off offset:2048 nt
	v_addc_co_u32_e32 v23, vcc, -1, v99, vcc
	global_load_dwordx2 v[32:33], v[22:23], off nt
	global_load_dwordx2 v[102:103], v[2:3], off offset:2560 nt
	v_add_co_u32_e32 v22, vcc, 0xe6000c00, v98
	s_mov_b64 s[0:1], 0
	s_nop 0
	v_addc_co_u32_e32 v23, vcc, -1, v99, vcc
	global_load_dwordx2 v[106:107], v[22:23], off nt
	global_load_dwordx2 v[108:109], v[2:3], off offset:3072 nt
	v_add_co_u32_e32 v22, vcc, 0xe6000e00, v98
	s_waitcnt lgkmcnt(0)
	s_waitcnt vmcnt(13)
	v_lshlrev_b32_e32 v58, 16, v6
	v_addc_co_u32_e32 v23, vcc, -1, v99, vcc
	global_load_dwordx2 v[110:111], v[22:23], off nt
	global_load_dwordx2 v[112:113], v[2:3], off offset:3584 nt
	v_and_b32_e32 v59, 0xffff0000, v6
	v_lshlrev_b32_e32 v60, 16, v7
	v_and_b32_e32 v61, 0xffff0000, v7
	s_waitcnt vmcnt(14)
	v_lshlrev_b32_e32 v50, 16, v8
	v_and_b32_e32 v51, 0xffff0000, v8
	v_lshlrev_b32_e32 v52, 16, v9
	v_and_b32_e32 v53, 0xffff0000, v9
	s_waitcnt vmcnt(13)
	v_lshlrev_b32_e32 v42, 16, v12
	v_and_b32_e32 v43, 0xffff0000, v12
	v_lshlrev_b32_e32 v44, 16, v13
	v_and_b32_e32 v45, 0xffff0000, v13
	s_waitcnt vmcnt(12)
	v_lshlrev_b32_e32 v22, 16, v14
	s_waitcnt vmcnt(11)
	v_lshlrev_b32_e32 v62, 16, v4
	v_and_b32_e32 v63, 0xffff0000, v4
	v_lshlrev_b32_e32 v64, 16, v5
	v_and_b32_e32 v65, 0xffff0000, v5
	s_waitcnt vmcnt(10)
	v_lshlrev_b32_e32 v54, 16, v10
	v_and_b32_e32 v55, 0xffff0000, v10
	v_lshlrev_b32_e32 v56, 16, v11
	v_and_b32_e32 v57, 0xffff0000, v11
	s_waitcnt vmcnt(9)
	v_lshlrev_b32_e32 v46, 16, v16
	v_and_b32_e32 v47, 0xffff0000, v16
	v_lshlrev_b32_e32 v48, 16, v17
	v_and_b32_e32 v49, 0xffff0000, v17
	s_waitcnt vmcnt(8)
	v_lshlrev_b32_e32 v26, 16, v18
	v_and_b32_e32 v27, 0xffff0000, v18
	v_lshlrev_b32_e32 v28, 16, v19
	v_and_b32_e32 v29, 0xffff0000, v19
	v_and_b32_e32 v23, 0xffff0000, v14
	v_lshlrev_b32_e32 v24, 16, v15
	v_and_b32_e32 v25, 0xffff0000, v15
	s_waitcnt vmcnt(7)
	v_lshlrev_b32_e32 v34, 16, v20
	v_and_b32_e32 v35, 0xffff0000, v20
	v_lshlrev_b32_e32 v36, 16, v21
	v_and_b32_e32 v37, 0xffff0000, v21
	s_waitcnt vmcnt(6)
	v_lshlrev_b32_e32 v38, 16, v30
	v_and_b32_e32 v39, 0xffff0000, v30
	v_lshlrev_b32_e32 v40, 16, v31
	v_and_b32_e32 v41, 0xffff0000, v31
	s_waitcnt vmcnt(5)
	v_lshlrev_b32_e32 v14, 16, v32
	v_and_b32_e32 v15, 0xffff0000, v32
	v_lshlrev_b32_e32 v16, 16, v33
	v_and_b32_e32 v17, 0xffff0000, v33
	s_waitcnt vmcnt(4)
	v_lshlrev_b32_e32 v30, 16, v102
	v_and_b32_e32 v31, 0xffff0000, v102
	v_lshlrev_b32_e32 v32, 16, v103
	v_and_b32_e32 v33, 0xffff0000, v103
	s_waitcnt vmcnt(3)
	v_lshlrev_b32_e32 v6, 16, v106
	v_and_b32_e32 v7, 0xffff0000, v106
	v_lshlrev_b32_e32 v8, 16, v107
	v_and_b32_e32 v9, 0xffff0000, v107
	s_waitcnt vmcnt(2)
	v_lshlrev_b32_e32 v18, 16, v108
	v_and_b32_e32 v19, 0xffff0000, v108
	v_lshlrev_b32_e32 v20, 16, v109
	v_and_b32_e32 v21, 0xffff0000, v109
	s_waitcnt lgkmcnt(0)
	s_waitcnt vmcnt(1)
	v_lshlrev_b32_e32 v2, 16, v110
	v_and_b32_e32 v3, 0xffff0000, v110
	v_lshlrev_b32_e32 v4, 16, v111
	v_and_b32_e32 v5, 0xffff0000, v111
	s_waitcnt vmcnt(0)
	v_lshlrev_b32_e32 v10, 16, v112
	v_and_b32_e32 v11, 0xffff0000, v112
	v_lshlrev_b32_e32 v12, 16, v113
	v_and_b32_e32 v13, 0xffff0000, v113
.LBB0_794:
	s_andn2_b64 vcc, exec, s[0:1]
	s_cbranch_vccnz .LBB0_796
	v_lshl_add_u64 v[2:3], v[96:97], 0, v[0:1]
	v_lshl_add_u64 v[4:5], v[104:105], 2, v[94:95]
	global_load_dwordx4 v[62:65], v[2:3], off nt
	global_load_dwordx4 v[54:57], v[2:3], off offset:1024 nt
	global_load_dwordx4 v[58:61], v[4:5], off nt
	global_load_dwordx4 v[50:53], v[4:5], off offset:1024 nt
	global_load_dwordx4 v[46:49], v[2:3], off offset:2048 nt
	s_waitcnt lgkmcnt(0)
	global_load_dwordx4 v[26:29], v[2:3], off offset:3072 nt
	global_load_dwordx4 v[42:45], v[4:5], off offset:2048 nt
	global_load_dwordx4 v[22:25], v[4:5], off offset:3072 nt
	v_add_co_u32_e32 v2, vcc, 0x1000, v2
	s_nop 1
	v_addc_co_u32_e32 v3, vcc, 0, v3, vcc
	v_add_co_u32_e32 v10, vcc, 0x1000, v4
	s_nop 1
	v_addc_co_u32_e32 v11, vcc, 0, v5, vcc
	global_load_dwordx4 v[34:37], v[2:3], off nt
	global_load_dwordx4 v[14:17], v[2:3], off offset:1024 nt
	global_load_dwordx4 v[38:41], v[10:11], off nt
	global_load_dwordx4 v[30:33], v[10:11], off offset:1024 nt
	global_load_dwordx4 v[6:9], v[2:3], off offset:2048 nt
	s_nop 0
	global_load_dwordx4 v[2:5], v[2:3], off offset:3072 nt
	s_nop 0
	global_load_dwordx4 v[18:21], v[10:11], off offset:2048 nt
	s_nop 0
	global_load_dwordx4 v[10:13], v[10:11], off offset:3072 nt
; __device__ __forceinline__ float bflo(unsigned w) { return __uint_as_float(w << 16); }
; __device__ __forceinline__ float bfhi(unsigned w) { return __uint_as_float(w & 0xffff0000u); }
; __device__ __forceinline__ void ln_phase(const Params& p, const int layer, const int row_lo, const int row_hi, const int wg_id, const int n_wg) {
;     ...
;         const v2u* ob0 = (const v2u*)(OB + (size_t)m0 * DM) + lane; const v2u* ob1 = (const v2u*)(OB + (size_t)m1 * DM) + lane;
;         f32x4 v0[8], v1[8]; v2u w0[8], w1[8]; float s0 = 0.f, s1 = 0.f;
;         if (layer == 0) {
;             const f32x4* xr0 = (const f32x4*)((m0 < NP) ? p.in[0] + (size_t)m0 * DM : p.in[1] + (size_t)(m0 - NP) * DM) + lane;
;             const f32x4* xr1 = (const f32x4*)((m1 < NP) ? p.in[0] + (size_t)m1 * DM : p.in[1] + (size_t)(m1 - NP) * DM) + lane;
; #pragma unroll
;             for (int j = 0; j < 8; ++j) { v0[j] = xr0[64 * j]; v1[j] = xr1[64 * j]; w0[j] = ob0[64 * j]; w1[j] = ob1[64 * j]; }
;         } else {
;             const v2u* xb0 = (const v2u*)(XB + (size_t)m0 * DM) + lane; const v2u* xb1 = (const v2u*)(XB + (size_t)m1 * DM) + lane;
;             v2u a0[8], a1[8];
; #pragma unroll
;             for (int j = 0; j < 8; ++j) { a0[j] = xb0[64 * j]; a1[j] = xb1[64 * j]; w0[j] = ob0[64 * j]; w1[j] = ob1[64 * j]; }
; #pragma unroll
;             for (int j = 0; j < 8; ++j) { v0[j] = (f32x4){bflo(a0[j].x), bfhi(a0[j].x), bflo(a0[j].y), bfhi(a0[j].y)}; v1[j] = (f32x4){bflo(a1[j].x), bfhi(a1[j].x), bflo(a1[j].y), bfhi(a1[j].y)}; }
;         }
; #pragma unroll
;         for (int j = 0; j < 8; ++j) { v0[j] = v0[j] * DN_ALPHA + (f32x4){bflo(w0[j].x), bfhi(w0[j].x), bflo(w0[j].y), bfhi(w0[j].y)};
;             v1[j] = v1[j] * DN_ALPHA + (f32x4){bflo(w1[j].x), bfhi(w1[j].x), bflo(w1[j].y), bfhi(w1[j].y)};
;             s0 += (v0[j].x + v0[j].y) + (v0[j].z + v0[j].w); s1 += (v1[j].x + v1[j].y) + (v1[j].z + v1[j].w); }
.LBB0_796:
	v_lshlrev_b64 v[102:103], 1, v[104:105]
	v_lshl_add_u64 v[110:111], v[68:69], 0, v[102:103]
	global_load_dwordx2 v[118:119], v[98:99], off offset:3584 nt
	global_load_dwordx2 v[120:121], v[98:99], off offset:3072 nt
	global_load_dwordx2 v[122:123], v[98:99], off offset:2560 nt
	global_load_dwordx2 v[126:127], v[98:99], off offset:2048 nt
	global_load_dwordx2 v[130:131], v[98:99], off offset:1536 nt
	global_load_dwordx2 v[106:107], v[98:99], off offset:1024 nt
	global_load_dwordx2 v[138:139], v[98:99], off offset:512 nt
	global_load_dwordx2 v[112:113], v[98:99], off nt
	global_load_dwordx2 v[140:141], v[110:111], off nt
	global_load_dwordx2 v[148:149], v[110:111], off offset:512 nt
	global_load_dwordx2 v[108:109], v[110:111], off offset:1024 nt
	global_load_dwordx2 v[136:137], v[110:111], off offset:1536 nt
	global_load_dwordx2 v[134:135], v[110:111], off offset:2048 nt
	global_load_dwordx2 v[132:133], v[110:111], off offset:2560 nt
	global_load_dwordx2 v[128:129], v[110:111], off offset:3072 nt
	global_load_dwordx2 v[124:125], v[110:111], off offset:3584 nt
	v_lshl_add_u64 v[104:105], v[104:105], 2, v[72:73]
	s_waitcnt lgkmcnt(0)
	s_waitcnt vmcnt(8)
	v_lshlrev_b32_e32 v110, 16, v112
	v_and_b32_e32 v111, 0xffff0000, v112
	v_lshlrev_b32_e32 v112, 16, v113
	v_and_b32_e32 v113, 0xffff0000, v113
	v_pk_fma_f32 v[114:115], v[64:65], s[4:5], v[112:113] op_sel_hi:[1,0,1]
	v_pk_fma_f32 v[116:117], v[62:63], s[4:5], v[110:111] op_sel_hi:[1,0,1]
	s_waitcnt vmcnt(7)
	v_lshlrev_b32_e32 v62, 16, v140
	v_and_b32_e32 v63, 0xffff0000, v140
	v_lshlrev_b32_e32 v64, 16, v141
	v_and_b32_e32 v65, 0xffff0000, v141
	v_pk_fma_f32 v[110:111], v[60:61], s[4:5], v[64:65] op_sel_hi:[1,0,1]
	v_pk_fma_f32 v[112:113], v[58:59], s[4:5], v[62:63] op_sel_hi:[1,0,1]
	v_lshlrev_b32_e32 v58, 16, v138
	v_and_b32_e32 v59, 0xffff0000, v138
	v_lshlrev_b32_e32 v60, 16, v139
	v_and_b32_e32 v61, 0xffff0000, v139
	v_pk_fma_f32 v[56:57], v[56:57], s[4:5], v[60:61] op_sel_hi:[1,0,1]
	v_pk_fma_f32 v[54:55], v[54:55], s[4:5], v[58:59] op_sel_hi:[1,0,1]
	s_waitcnt vmcnt(6)
	v_lshlrev_b32_e32 v58, 16, v148
	v_and_b32_e32 v59, 0xffff0000, v148
	v_lshlrev_b32_e32 v60, 16, v149
	v_and_b32_e32 v61, 0xffff0000, v149
	v_pk_fma_f32 v[52:53], v[52:53], s[4:5], v[60:61] op_sel_hi:[1,0,1]
	v_pk_fma_f32 v[50:51], v[50:51], s[4:5], v[58:59] op_sel_hi:[1,0,1]
	v_mov_b32_e32 v58, v54
	v_mov_b32_e32 v59, v116
	v_mov_b32_e32 v60, v55
	v_mov_b32_e32 v61, v117
	v_pk_add_f32 v[58:59], v[58:59], v[60:61]
	v_mov_b32_e32 v60, v57
	v_mov_b32_e32 v61, v115
	v_mov_b32_e32 v62, v56
	v_mov_b32_e32 v63, v114
	v_pk_add_f32 v[60:61], v[60:61], v[62:63]
	v_mov_b32_e32 v62, v111
	v_pk_add_f32 v[58:59], v[58:59], v[60:61]
	v_mov_b32_e32 v60, v113
	v_add_f32_e32 v59, 0, v59
	v_add_f32_e32 v139, v58, v59
	v_mov_b32_e32 v58, v112
	v_mov_b32_e32 v59, v50
	v_mov_b32_e32 v61, v51
	v_pk_add_f32 v[58:59], v[58:59], v[60:61]
	v_mov_b32_e32 v60, v110
	v_mov_b32_e32 v61, v52
	v_mov_b32_e32 v63, v53
	v_pk_add_f32 v[60:61], v[60:61], v[62:63]
	s_nop 0
	v_pk_add_f32 v[58:59], v[58:59], v[60:61]
	v_lshlrev_b32_e32 v60, 16, v107
	v_add_f32_e32 v58, 0, v58
	v_add_f32_e32 v140, v58, v59
	v_lshlrev_b32_e32 v58, 16, v106
	v_and_b32_e32 v59, 0xffff0000, v106
	v_and_b32_e32 v61, 0xffff0000, v107
	v_pk_fma_f32 v[46:47], v[46:47], s[4:5], v[58:59] op_sel_hi:[1,0,1]
	v_pk_fma_f32 v[48:49], v[48:49], s[4:5], v[60:61] op_sel_hi:[1,0,1]
	s_waitcnt vmcnt(5)
	v_lshlrev_b32_e32 v58, 16, v108
	v_and_b32_e32 v59, 0xffff0000, v108
	v_lshlrev_b32_e32 v60, 16, v109
	v_and_b32_e32 v61, 0xffff0000, v109
	v_pk_fma_f32 v[108:109], v[44:45], s[4:5], v[60:61] op_sel_hi:[1,0,1]
	v_pk_fma_f32 v[106:107], v[42:43], s[4:5], v[58:59] op_sel_hi:[1,0,1]
	v_mov_b32_e32 v42, v46
	v_mov_b32_e32 v43, v49
	v_pk_mov_b32 v[44:45], v[46:47], v[48:49] op_sel:[1,0]
	s_nop 0
	v_pk_add_f32 v[42:43], v[42:43], v[44:45]
	v_mov_b32_e32 v44, v106
	v_pk_add_f32 v[148:149], v[42:43], v[42:43] op_sel_hi:[0,1]
	v_pk_mov_b32 v[42:43], v[106:107], v[108:109] op_sel:[1,0]
	v_mov_b32_e32 v45, v109
	v_pk_add_f32 v[42:43], v[42:43], v[44:45]
	v_lshlrev_b32_e32 v44, 16, v131
	v_pk_add_f32 v[150:151], v[42:43], v[42:43] op_sel:[0,1] op_sel_hi:[1,0]
	v_lshlrev_b32_e32 v42, 16, v130
	v_and_b32_e32 v43, 0xffff0000, v130
	v_and_b32_e32 v45, 0xffff0000, v131
	v_pk_fma_f32 v[64:65], v[28:29], s[4:5], v[44:45] op_sel_hi:[1,0,1]
	v_pk_fma_f32 v[62:63], v[26:27], s[4:5], v[42:43] op_sel_hi:[1,0,1]
	v_lshlrev_b32_e32 v42, 16, v126
	v_and_b32_e32 v43, 0xffff0000, v126
	v_lshlrev_b32_e32 v44, 16, v127
	v_and_b32_e32 v45, 0xffff0000, v127
	s_waitcnt vmcnt(4)
	v_lshlrev_b32_e32 v26, 16, v136
	v_and_b32_e32 v27, 0xffff0000, v136
	v_lshlrev_b32_e32 v28, 16, v137
	v_and_b32_e32 v29, 0xffff0000, v137
	v_pk_fma_f32 v[44:45], v[36:37], s[4:5], v[44:45] op_sel_hi:[1,0,1]
	v_pk_fma_f32 v[42:43], v[34:35], s[4:5], v[42:43] op_sel_hi:[1,0,1]
	v_pk_fma_f32 v[60:61], v[24:25], s[4:5], v[28:29] op_sel_hi:[1,0,1]
	v_pk_fma_f32 v[58:59], v[22:23], s[4:5], v[26:27] op_sel_hi:[1,0,1]
	v_add_f32_e32 v23, v62, v63
	v_add_f32_e32 v25, v65, v64
	s_waitcnt vmcnt(3)
; __device__ __forceinline__ float bflo(unsigned w) { return __uint_as_float(w << 16); }
; __device__ __forceinline__ float bfhi(unsigned w) { return __uint_as_float(w & 0xffff0000u); }
; __device__ __forceinline__ void ln_phase(const Params& p, const int layer, const int row_lo, const int row_hi, const int wg_id, const int n_wg) {
;     ...
;         for (int j = 0; j < 8; ++j) { v0[j] = v0[j] * DN_ALPHA + (f32x4){bflo(w0[j].x), bfhi(w0[j].x), bflo(w0[j].y), bfhi(w0[j].y)};
;             v1[j] = v1[j] * DN_ALPHA + (f32x4){bflo(w1[j].x), bfhi(w1[j].x), bflo(w1[j].y), bfhi(w1[j].y)};
;             s0 += (v0[j].x + v0[j].y) + (v0[j].z + v0[j].w); s1 += (v1[j].x + v1[j].y) + (v1[j].z + v1[j].w); }
;         const float mean0 = wave_sum(s0) * (1.f / DM), mean1 = wave_sum(s1) * (1.f / DM); float q0 = 0.f, q1 = 0.f;
; #pragma unroll
;         for (int j = 0; j < 8; ++j) { v0[j] = v0[j] - mean0; v1[j] = v1[j] - mean1;
;             q0 += (v0[j].x * v0[j].x + v0[j].y * v0[j].y) + (v0[j].z * v0[j].z + v0[j].w * v0[j].w); q1 += (v1[j].x * v1[j].x + v1[j].y * v1[j].y) + (v1[j].z * v1[j].z + v1[j].w * v1[j].w); }
	v_lshlrev_b32_e32 v34, 16, v134
	v_and_b32_e32 v35, 0xffff0000, v134
	v_lshlrev_b32_e32 v36, 16, v135
	v_and_b32_e32 v37, 0xffff0000, v135
	v_mov_b32_e32 v22, v42
	v_mov_b32_e32 v24, v43
	v_mov_b32_e32 v148, v45
	v_mov_b32_e32 v138, v44
	v_pk_fma_f32 v[40:41], v[40:41], s[4:5], v[36:37] op_sel_hi:[1,0,1]
	v_pk_fma_f32 v[38:39], v[38:39], s[4:5], v[34:35] op_sel_hi:[1,0,1]
	v_pk_add_f32 v[22:23], v[22:23], v[24:25]
	v_pk_add_f32 v[24:25], v[148:149], v[138:139]
	v_add_f32_e32 v26, v58, v59
	v_add_f32_e32 v28, v60, v61
	v_pk_add_f32 v[22:23], v[22:23], v[24:25]
	v_mov_b32_e32 v141, v38
	v_mov_b32_e32 v151, v39
	v_mov_b32_e32 v27, v40
	v_mov_b32_e32 v29, v41
	v_pk_add_f32 v[126:127], v[22:23], v[22:23] op_sel_hi:[0,1]
	v_pk_add_f32 v[22:23], v[140:141], v[150:151]
	v_pk_add_f32 v[24:25], v[26:27], v[28:29]
	s_nop 0
	v_pk_add_f32 v[22:23], v[22:23], v[24:25]
	v_lshlrev_b32_e32 v24, 16, v123
	v_pk_add_f32 v[130:131], v[22:23], v[22:23] op_sel:[0,1] op_sel_hi:[1,0]
	v_lshlrev_b32_e32 v22, 16, v122
	v_and_b32_e32 v23, 0xffff0000, v122
	v_and_b32_e32 v25, 0xffff0000, v123
	v_pk_fma_f32 v[34:35], v[14:15], s[4:5], v[22:23] op_sel_hi:[1,0,1]
	v_pk_fma_f32 v[36:37], v[16:17], s[4:5], v[24:25] op_sel_hi:[1,0,1]
	s_waitcnt vmcnt(2)
	v_lshlrev_b32_e32 v14, 16, v132
	v_and_b32_e32 v15, 0xffff0000, v132
	v_lshlrev_b32_e32 v16, 16, v133
	v_and_b32_e32 v17, 0xffff0000, v133
	v_pk_fma_f32 v[32:33], v[32:33], s[4:5], v[16:17] op_sel_hi:[1,0,1]
	v_pk_fma_f32 v[30:31], v[30:31], s[4:5], v[14:15] op_sel_hi:[1,0,1]
	v_mov_b32_e32 v14, v34
	v_mov_b32_e32 v15, v37
	v_pk_mov_b32 v[16:17], v[34:35], v[36:37] op_sel:[1,0]
	s_nop 0
	v_pk_add_f32 v[14:15], v[14:15], v[16:17]
	v_mov_b32_e32 v16, v30
	v_pk_add_f32 v[122:123], v[14:15], v[14:15] op_sel_hi:[0,1]
	v_pk_mov_b32 v[14:15], v[30:31], v[32:33] op_sel:[1,0]
	v_mov_b32_e32 v17, v33
	v_pk_add_f32 v[14:15], v[14:15], v[16:17]
	v_lshlrev_b32_e32 v16, 16, v121
	v_pk_add_f32 v[132:133], v[14:15], v[14:15] op_sel:[0,1] op_sel_hi:[1,0]
	v_lshlrev_b32_e32 v14, 16, v120
	v_and_b32_e32 v15, 0xffff0000, v120
	v_and_b32_e32 v17, 0xffff0000, v121
	v_pk_fma_f32 v[28:29], v[8:9], s[4:5], v[16:17] op_sel_hi:[1,0,1]
	v_pk_fma_f32 v[26:27], v[6:7], s[4:5], v[14:15] op_sel_hi:[1,0,1]
	s_waitcnt vmcnt(1)
	v_lshlrev_b32_e32 v8, 16, v129
	v_and_b32_e32 v9, 0xffff0000, v129
	v_lshlrev_b32_e32 v16, 16, v118
	v_and_b32_e32 v17, 0xffff0000, v118
	v_lshlrev_b32_e32 v14, 16, v119
	v_and_b32_e32 v15, 0xffff0000, v119
	v_lshlrev_b32_e32 v6, 16, v128
	v_and_b32_e32 v7, 0xffff0000, v128
	v_pk_fma_f32 v[24:25], v[20:21], s[4:5], v[8:9] op_sel_hi:[1,0,1]
	v_pk_fma_f32 v[14:15], v[4:5], s[4:5], v[14:15] op_sel_hi:[1,0,1]
	v_pk_fma_f32 v[20:21], v[2:3], s[4:5], v[16:17] op_sel_hi:[1,0,1]
	v_pk_fma_f32 v[22:23], v[18:19], s[4:5], v[6:7] op_sel_hi:[1,0,1]
	v_add_f32_e32 v7, v26, v27
	v_add_f32_e32 v9, v29, v28
	s_waitcnt vmcnt(0)
	v_lshlrev_b32_e32 v2, 16, v124
	v_and_b32_e32 v3, 0xffff0000, v124
	v_lshlrev_b32_e32 v4, 16, v125
	v_and_b32_e32 v5, 0xffff0000, v125
	v_mov_b32_e32 v6, v20
	v_mov_b32_e32 v8, v21
	v_mov_b32_e32 v122, v15
	v_mov_b32_e32 v126, v14
	v_pk_fma_f32 v[16:17], v[12:13], s[4:5], v[4:5] op_sel_hi:[1,0,1]
	v_pk_fma_f32 v[18:19], v[10:11], s[4:5], v[2:3] op_sel_hi:[1,0,1]
	v_pk_add_f32 v[2:3], v[6:7], v[8:9]
	v_pk_add_f32 v[4:5], v[122:123], v[126:127]
	v_add_f32_e32 v120, v22, v23
	v_add_f32_e32 v128, v24, v25
	v_pk_add_f32 v[2:3], v[2:3], v[4:5]
	v_mov_b32_e32 v131, v18
	v_mov_b32_e32 v133, v19
	v_mov_b32_e32 v121, v16
	v_mov_b32_e32 v129, v17
	v_add_f32_e32 v6, v2, v3
	v_pk_add_f32 v[2:3], v[130:131], v[132:133]
	v_pk_add_f32 v[4:5], v[120:121], v[128:129]
	s_nop 0
	v_pk_add_f32 v[2:3], v[2:3], v[4:5]
	s_nop 0
	v_add_f32_e32 v2, v2, v3
	ds_bpermute_b32 v3, v142, v6
	s_waitcnt lgkmcnt(0)
	v_add_f32_e32 v3, v6, v3
	ds_bpermute_b32 v4, v143, v3
	s_waitcnt lgkmcnt(0)
	v_add_f32_e32 v3, v3, v4
	ds_bpermute_b32 v4, v144, v3
	s_waitcnt lgkmcnt(0)
	v_add_f32_e32 v3, v3, v4
	ds_bpermute_b32 v4, v145, v3
	s_waitcnt lgkmcnt(0)
	v_add_f32_e32 v3, v3, v4
	ds_bpermute_b32 v4, v146, v3
	s_waitcnt lgkmcnt(0)
	v_add_f32_e32 v3, v3, v4
	ds_bpermute_b32 v4, v147, v3
	s_waitcnt lgkmcnt(0)
	v_add_f32_e32 v67, v3, v4
	ds_bpermute_b32 v3, v142, v2
	v_fmamk_f32 v117, v67, 0xba000000, v117
	v_fmac_f32_e32 v116, 0xba000000, v67
	v_fmamk_f32 v121, v67, 0xba000000, v55
	v_fmac_f32_e32 v54, 0xba000000, v67
	s_waitcnt lgkmcnt(0)
	v_add_f32_e32 v2, v2, v3
	ds_bpermute_b32 v3, v143, v2
	v_mov_b32_e32 v120, v117
	v_fmac_f32_e32 v114, 0xba000000, v67
	v_fmac_f32_e32 v56, 0xba000000, v67
	v_pk_mul_f32 v[4:5], v[120:121], v[120:121]
	s_waitcnt lgkmcnt(0)
	v_add_f32_e32 v2, v2, v3
	ds_bpermute_b32 v3, v144, v2
	v_fmamk_f32 v115, v67, 0xba000000, v115
	v_fmamk_f32 v127, v67, 0xba000000, v57
	v_mov_b32_e32 v126, v115
	v_fmamk_f32 v49, v67, 0xba000000, v49
	s_waitcnt lgkmcnt(0)
	v_add_f32_e32 v2, v2, v3
	ds_bpermute_b32 v3, v145, v2
	v_fmac_f32_e32 v48, 0xba000000, v67
	v_fmamk_f32 v47, v67, 0xba000000, v47
	v_fmac_f32_e32 v46, 0xba000000, v67
	v_fmac_f32_e32 v62, 0xba000000, v67
	s_waitcnt lgkmcnt(0)
	v_add_f32_e32 v2, v2, v3
	ds_bpermute_b32 v3, v146, v2
	v_fmac_f32_e32 v64, 0xba000000, v67
	v_fmamk_f32 v63, v67, 0xba000000, v63
	v_fmamk_f32 v65, v67, 0xba000000, v65
	v_fmamk_f32 v45, v67, 0xba000000, v45
	s_waitcnt lgkmcnt(0)
	v_add_f32_e32 v2, v2, v3
	ds_bpermute_b32 v3, v147, v2
	v_fmac_f32_e32 v44, 0xba000000, v67
	v_fmamk_f32 v43, v67, 0xba000000, v43
	v_fmac_f32_e32 v42, 0xba000000, v67
	v_fmamk_f32 v37, v67, 0xba000000, v37
	s_waitcnt lgkmcnt(0)
; __device__ __forceinline__ void ln_phase(const Params& p, const int layer, const int row_lo, const int row_hi, const int wg_id, const int n_wg) {
;     ...
;         for (int j = 0; j < 8; ++j) { v0[j] = v0[j] - mean0; v1[j] = v1[j] - mean1;
;             q0 += (v0[j].x * v0[j].x + v0[j].y * v0[j].y) + (v0[j].z * v0[j].z + v0[j].w * v0[j].w); q1 += (v1[j].x * v1[j].x + v1[j].y * v1[j].y) + (v1[j].z * v1[j].z + v1[j].w * v1[j].w); }
;         const float rstd0 = 1.f / sqrtf(wave_sum(q0) * (1.f / DM) + LN_EPS), rstd1 = 1.f / sqrtf(wave_sum(q1) * (1.f / DM) + LN_EPS);
	v_add_f32_e32 v130, v2, v3
	v_mov_b32_e32 v2, v116
	v_mov_b32_e32 v3, v54
	v_pk_fma_f32 v[2:3], v[2:3], v[2:3], v[4:5]
	v_mov_b32_e32 v4, v114
	v_mov_b32_e32 v5, v56
	v_fmamk_f32 v113, v130, 0xba000000, v113
	v_pk_mul_f32 v[4:5], v[4:5], v[4:5]
	v_fmamk_f32 v111, v130, 0xba000000, v111
	v_fmac_f32_e32 v112, 0xba000000, v130
	v_fmamk_f32 v123, v130, 0xba000000, v51
	v_fmac_f32_e32 v50, 0xba000000, v130
	v_pk_fma_f32 v[4:5], v[126:127], v[126:127], v[4:5]
	v_mov_b32_e32 v122, v113
	v_fmac_f32_e32 v110, 0xba000000, v130
	v_fmamk_f32 v125, v130, 0xba000000, v53
	v_fmac_f32_e32 v52, 0xba000000, v130
	v_pk_add_f32 v[2:3], v[2:3], v[4:5]
	v_mov_b32_e32 v4, v112
	v_mov_b32_e32 v5, v50
	v_pk_mul_f32 v[6:7], v[122:123], v[122:123]
	v_mov_b32_e32 v124, v111
	v_pk_fma_f32 v[4:5], v[4:5], v[4:5], v[6:7]
	v_mov_b32_e32 v6, v110
	v_mov_b32_e32 v7, v52
	v_pk_mul_f32 v[8:9], v[124:125], v[124:125]
	v_fmamk_f32 v109, v130, 0xba000000, v109
	v_pk_fma_f32 v[6:7], v[6:7], v[6:7], v[8:9]
	v_pk_mul_f32 v[8:9], v[46:47], v[46:47]
	v_pk_add_f32 v[4:5], v[4:5], v[6:7]
	v_pk_mul_f32 v[6:7], v[48:49], v[48:49]
	v_fmac_f32_e32 v108, 0xba000000, v130
	v_fmamk_f32 v107, v130, 0xba000000, v107
	v_fmac_f32_e32 v106, 0xba000000, v130
	v_pk_mov_b32 v[10:11], v[8:9], v[6:7] op_sel:[1,0]
	v_mov_b32_e32 v9, v7
	v_pk_add_f32 v[2:3], v[2:3], v[2:3] op_sel_hi:[0,1]
	v_pk_add_f32 v[6:7], v[8:9], v[10:11]
	v_pk_mul_f32 v[8:9], v[108:109], v[108:109]
	v_pk_mul_f32 v[10:11], v[106:107], v[106:107]
	v_mul_f32_e32 v2, v62, v62
	v_pk_mov_b32 v[12:13], v[10:11], v[8:9] op_sel:[1,0]
	v_mov_b32_e32 v11, v9
	v_pk_add_f32 v[8:9], v[12:13], v[10:11]
	v_fmac_f32_e32 v58, 0xba000000, v130
	v_pk_fma_f32 v[10:11], v[62:63], v[62:63], v[2:3] op_sel_hi:[1,1,0]
	v_mul_f32_e32 v2, v64, v64
	v_fmac_f32_e32 v60, 0xba000000, v130
	v_fmamk_f32 v59, v130, 0xba000000, v59
	v_pk_fma_f32 v[12:13], v[64:65], v[64:65], v[2:3] op_sel_hi:[1,1,0]
	v_mul_f32_e32 v2, v58, v58
	v_fmamk_f32 v61, v130, 0xba000000, v61
	v_pk_fma_f32 v[118:119], v[58:59], v[58:59], v[2:3] op_sel_hi:[1,1,0]
	v_mul_f32_e32 v2, v60, v60
	v_pk_add_f32 v[4:5], v[4:5], v[4:5] op_sel_hi:[0,1]
	v_pk_add_f32 v[6:7], v[6:7], v[6:7] op_sel_hi:[0,1]
	v_pk_add_f32 v[8:9], v[8:9], v[8:9] op_sel_hi:[0,1]
	v_pk_fma_f32 v[128:129], v[60:61], v[60:61], v[2:3] op_sel_hi:[1,1,0]
	v_fmamk_f32 v41, v130, 0xba000000, v41
	v_fmac_f32_e32 v40, 0xba000000, v130
	v_fmamk_f32 v39, v130, 0xba000000, v39
	v_fmac_f32_e32 v38, 0xba000000, v130
	v_mul_f32_e32 v2, v44, v44
	v_mul_f32_e32 v6, v45, v45
	v_mul_f32_e32 v118, v38, v38
	v_mul_f32_e32 v128, v39, v39
	v_mul_f32_e32 v8, v40, v40
	v_mul_f32_e32 v4, v41, v41
	v_mul_f32_e32 v10, v42, v42
	v_mul_f32_e32 v12, v43, v43
	v_pk_add_f32 v[2:3], v[6:7], v[2:3]
	v_pk_add_f32 v[6:7], v[118:119], v[128:129]
	v_pk_add_f32 v[4:5], v[8:9], v[4:5]
	v_fmac_f32_e32 v36, 0xba000000, v67
	v_fmamk_f32 v35, v67, 0xba000000, v35
	v_fmac_f32_e32 v34, 0xba000000, v67
	v_pk_add_f32 v[10:11], v[10:11], v[12:13]
	v_pk_add_f32 v[4:5], v[6:7], v[4:5]
	v_pk_mul_f32 v[6:7], v[36:37], v[36:37]
	v_pk_mul_f32 v[8:9], v[34:35], v[34:35]
	v_pk_add_f32 v[2:3], v[10:11], v[2:3]
	v_fmamk_f32 v33, v130, 0xba000000, v33
	v_fmac_f32_e32 v32, 0xba000000, v130
	v_fmamk_f32 v31, v130, 0xba000000, v31
	v_fmac_f32_e32 v30, 0xba000000, v130
	v_pk_mov_b32 v[10:11], v[8:9], v[6:7] op_sel:[1,0]
	v_mov_b32_e32 v9, v7
	v_pk_add_f32 v[2:3], v[2:3], v[2:3] op_sel_hi:[0,1]
	v_pk_add_f32 v[6:7], v[8:9], v[10:11]
	v_pk_mul_f32 v[8:9], v[32:33], v[32:33]
	v_pk_mul_f32 v[10:11], v[30:31], v[30:31]
	v_fmac_f32_e32 v26, 0xba000000, v67
	v_pk_mov_b32 v[12:13], v[10:11], v[8:9] op_sel:[1,0]
	v_mov_b32_e32 v11, v9
	v_fmac_f32_e32 v28, 0xba000000, v67
	v_fmamk_f32 v27, v67, 0xba000000, v27
	v_mul_f32_e32 v2, v26, v26
	v_pk_add_f32 v[8:9], v[12:13], v[10:11]
	v_fmamk_f32 v29, v67, 0xba000000, v29
	v_fmac_f32_e32 v22, 0xba000000, v130
	v_pk_fma_f32 v[10:11], v[26:27], v[26:27], v[2:3] op_sel_hi:[1,1,0]
	v_mul_f32_e32 v2, v28, v28
	v_fmac_f32_e32 v24, 0xba000000, v130
	v_fmamk_f32 v23, v130, 0xba000000, v23
	v_pk_fma_f32 v[12:13], v[28:29], v[28:29], v[2:3] op_sel_hi:[1,1,0]
	v_mul_f32_e32 v2, v22, v22
	v_pk_add_f32 v[6:7], v[6:7], v[6:7] op_sel_hi:[0,1]
	v_fmamk_f32 v25, v130, 0xba000000, v25
	v_pk_fma_f32 v[118:119], v[22:23], v[22:23], v[2:3] op_sel_hi:[1,1,0]
	v_mul_f32_e32 v2, v24, v24
	v_fmamk_f32 v15, v67, 0xba000000, v15
	v_fmac_f32_e32 v14, 0xba000000, v67
	v_fmamk_f32 v21, v67, 0xba000000, v21
	v_fmac_f32_e32 v20, 0xba000000, v67
	v_pk_fma_f32 v[128:129], v[24:25], v[24:25], v[2:3] op_sel_hi:[1,1,0]
	v_mul_f32_e32 v10, v20, v20
	v_mul_f32_e32 v12, v21, v21
	v_mul_f32_e32 v2, v14, v14
	v_mul_f32_e32 v6, v15, v15
	v_pk_add_f32 v[4:5], v[4:5], v[4:5] op_sel_hi:[0,1]
	v_pk_add_f32 v[8:9], v[8:9], v[8:9] op_sel_hi:[0,1]
	v_fmamk_f32 v17, v130, 0xba000000, v17
	v_fmac_f32_e32 v16, 0xba000000, v130
	v_fmamk_f32 v19, v130, 0xba000000, v19
	v_fmac_f32_e32 v18, 0xba000000, v130
	v_pk_add_f32 v[10:11], v[10:11], v[12:13]
	v_pk_add_f32 v[2:3], v[6:7], v[2:3]
	v_mul_f32_e32 v118, v18, v18
	v_pk_add_f32 v[2:3], v[10:11], v[2:3]
	v_mul_f32_e32 v128, v19, v19
	v_mul_f32_e32 v8, v16, v16
	v_mul_f32_e32 v4, v17, v17
	v_add_f32_e32 v6, v2, v3
	v_pk_add_f32 v[2:3], v[118:119], v[128:129]
	v_pk_add_f32 v[4:5], v[8:9], v[4:5]
	v_lshl_add_u64 v[118:119], v[100:101], 0, v[0:1]
	v_pk_add_f32 v[2:3], v[2:3], v[4:5]
	s_nop 0
	v_add_f32_e32 v2, v2, v3
	ds_bpermute_b32 v3, v142, v6
	s_waitcnt lgkmcnt(0)
; __device__ __forceinline__ unsigned pk2(float lo, float hi) { return f2bf(lo) | (f2bf(hi) << 16); }
; __device__ __forceinline__ void ln_phase(const Params& p, const int layer, const int row_lo, const int row_hi, const int wg_id, const int n_wg) {
;     ...
;         const float mean0 = wave_sum(s0) * (1.f / DM), mean1 = wave_sum(s1) * (1.f / DM); float q0 = 0.f, q1 = 0.f;
; #pragma unroll
;         for (int j = 0; j < 8; ++j) { v0[j] = v0[j] - mean0; v1[j] = v1[j] - mean1;
;             q0 += (v0[j].x * v0[j].x + v0[j].y * v0[j].y) + (v0[j].z * v0[j].z + v0[j].w * v0[j].w); q1 += (v1[j].x * v1[j].x + v1[j].y * v1[j].y) + (v1[j].z * v1[j].z + v1[j].w * v1[j].w); }
;         const float rstd0 = 1.f / sqrtf(wave_sum(q0) * (1.f / DM) + LN_EPS), rstd1 = 1.f / sqrtf(wave_sum(q1) * (1.f / DM) + LN_EPS);
;         f32x4* zr0 = (f32x4*)(Z + (size_t)m0 * DM) + lane; f32x4* zr1 = (f32x4*)(Z + (size_t)m1 * DM) + lane;
;         unsigned long long* o80 = (unsigned long long*)(XB + (size_t)m0 * DM) + lane; unsigned long long* o81 = (unsigned long long*)(XB + (size_t)m1 * DM) + lane;
; #pragma unroll
;         for (int j = 0; j < 8; ++j) { const f32x4 gv = *((const f32x4*)g + lane + 64 * j), bv = *((const f32x4*)bb + lane + 64 * j);
;             const f32x4 y0 = v0[j] * rstd0 * gv + bv, y1 = v1[j] * rstd1 * gv + bv;
;             if (layer == 0) { o80[64 * j] = (unsigned long long)pk2(y0.x, y0.y) | ((unsigned long long)pk2(y0.z, y0.w) << 32);
;                 if (ok1) o81[64 * j] = (unsigned long long)pk2(y1.x, y1.y) | ((unsigned long long)pk2(y1.z, y1.w) << 32); }
;             else { zr0[64 * j] = y0; if (ok1) zr1[64 * j] = y1; } }
	v_add_f32_e32 v3, v6, v3
	ds_bpermute_b32 v4, v143, v3
	s_waitcnt lgkmcnt(0)
	v_add_f32_e32 v3, v3, v4
	ds_bpermute_b32 v4, v144, v3
	s_waitcnt lgkmcnt(0)
	v_add_f32_e32 v3, v3, v4
	ds_bpermute_b32 v4, v145, v3
	s_waitcnt lgkmcnt(0)
	v_add_f32_e32 v3, v3, v4
	ds_bpermute_b32 v4, v146, v3
	s_waitcnt lgkmcnt(0)
	v_add_f32_e32 v3, v3, v4
	ds_bpermute_b32 v4, v147, v3
	s_waitcnt lgkmcnt(0)
	v_add_f32_e32 v3, v3, v4
	v_fmamk_f32 v3, v3, 0x3a000000, v218
	v_cmp_gt_f32_e32 vcc, s12, v3
	v_mul_f32_e32 v4, 0x4f800000, v3
	s_nop 0
	v_cndmask_b32_e32 v3, v3, v4, vcc
	v_sqrt_f32_e32 v4, v3
	s_nop 0
	v_add_u32_e32 v5, -1, v4
	v_fma_f32 v6, -v5, v4, v3
	v_cmp_ge_f32_e64 s[0:1], 0, v6
	v_add_u32_e32 v6, 1, v4
	s_nop 0
	v_cndmask_b32_e64 v5, v4, v5, s[0:1]
	v_fma_f32 v4, -v6, v4, v3
	v_cmp_lt_f32_e64 s[0:1], 0, v4
	s_nop 1
	v_cndmask_b32_e64 v4, v5, v6, s[0:1]
	v_mul_f32_e32 v5, 0x37800000, v4
	v_cndmask_b32_e32 v4, v4, v5, vcc
	v_cmp_class_f32_e32 vcc, v3, v219
	s_nop 1
	v_cndmask_b32_e32 v3, v4, v3, vcc
	v_div_scale_f32 v4, s[0:1], v3, v3, 1.0
	v_rcp_f32_e32 v5, v4
	s_nop 0
	v_fma_f32 v6, -v4, v5, 1.0
	v_fmac_f32_e32 v5, v6, v5
	v_div_scale_f32 v6, vcc, 1.0, v3, 1.0
	v_mul_f32_e32 v7, v6, v5
	v_fma_f32 v8, -v4, v7, v6
	v_fmac_f32_e32 v7, v8, v5
	v_fma_f32 v4, -v4, v7, v6
	v_div_fmas_f32 v4, v4, v5, v7
	v_div_fixup_f32 v120, v4, v3, 1.0
	ds_bpermute_b32 v3, v142, v2
	v_pk_mul_f32 v[10:11], v[116:117], v[120:121] op_sel_hi:[1,0]
	v_pk_mul_f32 v[12:13], v[114:115], v[120:121] op_sel_hi:[1,0]
	s_waitcnt lgkmcnt(0)
	v_add_f32_e32 v2, v2, v3
	ds_bpermute_b32 v3, v143, v2
	s_waitcnt lgkmcnt(0)
	v_add_f32_e32 v2, v2, v3
	ds_bpermute_b32 v3, v144, v2
	s_waitcnt lgkmcnt(0)
	v_add_f32_e32 v2, v2, v3
	ds_bpermute_b32 v3, v145, v2
	s_waitcnt lgkmcnt(0)
	v_add_f32_e32 v2, v2, v3
	ds_bpermute_b32 v3, v146, v2
	s_waitcnt lgkmcnt(0)
	v_add_f32_e32 v2, v2, v3
	ds_bpermute_b32 v3, v147, v2
	s_waitcnt lgkmcnt(0)
	v_add_f32_e32 v2, v2, v3
	v_fmamk_f32 v2, v2, 0x3a000000, v218
	v_cmp_gt_f32_e32 vcc, s12, v2
	v_mul_f32_e32 v3, 0x4f800000, v2
	s_nop 0
	v_cndmask_b32_e32 v2, v2, v3, vcc
	v_sqrt_f32_e32 v3, v2
	s_nop 0
	v_add_u32_e32 v4, -1, v3
	v_fma_f32 v5, -v4, v3, v2
	v_cmp_ge_f32_e64 s[0:1], 0, v5
	v_add_u32_e32 v5, 1, v3
	s_nop 0
	v_cndmask_b32_e64 v4, v3, v4, s[0:1]
	v_fma_f32 v3, -v5, v3, v2
	v_cmp_lt_f32_e64 s[0:1], 0, v3
	s_nop 1
	v_cndmask_b32_e64 v3, v4, v5, s[0:1]
	v_mul_f32_e32 v4, 0x37800000, v3
	v_cndmask_b32_e32 v3, v3, v4, vcc
	v_cmp_class_f32_e32 vcc, v2, v219
	s_nop 1
	v_cndmask_b32_e32 v2, v3, v2, vcc
	v_div_scale_f32 v3, s[0:1], v2, v2, 1.0
	v_rcp_f32_e32 v4, v3
	s_mov_b64 s[0:1], -1
	v_fma_f32 v5, -v3, v4, 1.0
	v_fmac_f32_e32 v4, v5, v4
	v_div_scale_f32 v5, vcc, 1.0, v2, 1.0
	v_mul_f32_e32 v6, v5, v4
	v_fma_f32 v7, -v3, v6, v5
	v_fmac_f32_e32 v6, v7, v4
	v_fma_f32 v3, -v3, v6, v5
	v_div_fmas_f32 v3, v3, v4, v6
	v_div_fixup_f32 v122, v3, v2, 1.0
	v_mov_b64_e32 v[2:3], v[152:153]
	v_mov_b64_e32 v[4:5], v[154:155]
	v_mov_b64_e32 v[6:7], v[184:185]
	v_mov_b64_e32 v[8:9], v[186:187]
	v_pk_mul_f32 v[112:113], v[112:113], v[122:123] op_sel_hi:[1,0]
	v_pk_mul_f32 v[110:111], v[110:111], v[122:123] op_sel_hi:[1,0]
	s_and_b64 vcc, exec, s[10:11]
	v_pk_fma_f32 v[12:13], v[4:5], v[12:13], v[8:9]
	v_pk_fma_f32 v[10:11], v[2:3], v[10:11], v[6:7]
	v_pk_fma_f32 v[4:5], v[4:5], v[110:111], v[8:9]
	v_pk_fma_f32 v[2:3], v[2:3], v[112:113], v[6:7]
	s_cbranch_vccz .LBB0_800
	global_store_dwordx4 v[118:119], v[10:13], off
	s_and_saveexec_b64 s[0:1], s[38:39]
	s_cbranch_execz .LBB0_799
	global_store_dwordx4 v[104:105], v[2:5], off

; __device__ __forceinline__ float bflo(unsigned w) { return __uint_as_float(w << 16); }
; __device__ __forceinline__ float bfhi(unsigned w) { return __uint_as_float(w & 0xffff0000u); }
; __device__ __forceinline__ void ln_phase(const Params& p, const int layer, const int row_lo, const int row_hi, const int wg_id, const int n_wg) {
;     ...
;     for (int m0 = row_lo + gw; m0 < row_hi; m0 += 2 * NGW) {
;         const int m1r = m0 + NGW; const bool ok1 = m1r < row_hi; const int m1 = ok1 ? m1r : m0;
;         const v2u* ob0 = (const v2u*)(OB + (size_t)m0 * DM) + lane; const v2u* ob1 = (const v2u*)(OB + (size_t)m1 * DM) + lane;
;         f32x4 v0[8], v1[8]; v2u w0[8], w1[8]; float s0 = 0.f, s1 = 0.f;
;         if (layer == 0) {
;             const f32x4* xr0 = (const f32x4*)((m0 < NP) ? p.in[0] + (size_t)m0 * DM : p.in[1] + (size_t)(m0 - NP) * DM) + lane;
;             const f32x4* xr1 = (const f32x4*)((m1 < NP) ? p.in[0] + (size_t)m1 * DM : p.in[1] + (size_t)(m1 - NP) * DM) + lane;
; #pragma unroll
;             for (int j = 0; j < 8; ++j) { v0[j] = xr0[64 * j]; v1[j] = xr1[64 * j]; w0[j] = ob0[64 * j]; w1[j] = ob1[64 * j]; }
;         } else {
;             const v2u* xb0 = (const v2u*)(XB + (size_t)m0 * DM) + lane; const v2u* xb1 = (const v2u*)(XB + (size_t)m1 * DM) + lane;
;             v2u a0[8], a1[8];
; #pragma unroll
;             for (int j = 0; j < 8; ++j) { a0[j] = xb0[64 * j]; a1[j] = xb1[64 * j]; w0[j] = ob0[64 * j]; w1[j] = ob1[64 * j]; }
; #pragma unroll
;             for (int j = 0; j < 8; ++j) { v0[j] = (f32x4){bflo(a0[j].x), bfhi(a0[j].x), bflo(a0[j].y), bfhi(a0[j].y)}; v1[j] = (f32x4){bflo(a1[j].x), bfhi(a1[j].x), bflo(a1[j].y), bfhi(a1[j].y)}; }
;         }
.LBB0_1029:
	v_readlane_b32 s0, v249, 62
	s_and_b64 vcc, exec, s[10:11]
	s_nop 0
	v_add_u32_e32 v0, s0, v66
	s_movk_i32 s0, 0x2400
	v_cmp_gt_i32_e64 s[38:39], s0, v0
	s_mov_b64 s[0:1], -1
	s_nop 0
	v_cndmask_b32_e64 v104, v66, v0, s[38:39]
	v_ashrrev_i32_e32 v105, 31, v104
	v_lshlrev_b64 v[102:103], 11, v[104:105]
	s_cbranch_vccz .LBB0_1031
	v_add_co_u32_e32 v4, vcc, 0xe6000000, v96
	v_lshl_add_u64 v[2:3], v[102:103], 1, v[70:71]
	s_nop 0
	v_addc_co_u32_e32 v5, vcc, -1, v97, vcc
	v_add_co_u32_e32 v10, vcc, 0xe6000200, v96
	global_load_dwordx2 v[6:7], v[2:3], off nt
	global_load_dwordx2 v[8:9], v[2:3], off offset:512 nt
	global_load_dwordx2 v[12:13], v[2:3], off offset:1024 nt
	v_addc_co_u32_e32 v11, vcc, -1, v97, vcc
	v_add_co_u32_e32 v16, vcc, 0xe6000400, v96
	global_load_dwordx2 v[14:15], v[2:3], off offset:1536 nt
	s_nop 0
	global_load_dwordx2 v[4:5], v[4:5], off nt
	s_nop 0
	global_load_dwordx2 v[10:11], v[10:11], off nt
	v_addc_co_u32_e32 v17, vcc, -1, v97, vcc
	v_add_co_u32_e32 v18, vcc, 0xe6000600, v96
	global_load_dwordx2 v[16:17], v[16:17], off nt
	s_nop 0
	v_addc_co_u32_e32 v19, vcc, -1, v97, vcc
	v_add_co_u32_e32 v20, vcc, 0xe6000800, v96
	global_load_dwordx2 v[18:19], v[18:19], off nt
	s_nop 0
	v_addc_co_u32_e32 v21, vcc, -1, v97, vcc
	v_add_co_u32_e32 v22, vcc, 0xe6000a00, v96
	global_load_dwordx2 v[20:21], v[20:21], off nt
	s_nop 0
	global_load_dwordx2 v[30:31], v[2:3], off offset:2048 nt
	v_addc_co_u32_e32 v23, vcc, -1, v97, vcc
	global_load_dwordx2 v[32:33], v[22:23], off nt
	global_load_dwordx2 v[106:107], v[2:3], off offset:2560 nt
	v_add_co_u32_e32 v22, vcc, 0xe6000c00, v96
	s_mov_b64 s[0:1], 0
	s_nop 0
	v_addc_co_u32_e32 v23, vcc, -1, v97, vcc
	global_load_dwordx2 v[108:109], v[22:23], off nt
	global_load_dwordx2 v[110:111], v[2:3], off offset:3072 nt
	v_add_co_u32_e32 v22, vcc, 0xe6000e00, v96
	s_waitcnt lgkmcnt(0)
	s_waitcnt vmcnt(13)
	v_lshlrev_b32_e32 v58, 16, v6
	v_addc_co_u32_e32 v23, vcc, -1, v97, vcc
	global_load_dwordx2 v[112:113], v[22:23], off nt
	global_load_dwordx2 v[114:115], v[2:3], off offset:3584 nt
	v_and_b32_e32 v59, 0xffff0000, v6
	v_lshlrev_b32_e32 v60, 16, v7
	v_and_b32_e32 v61, 0xffff0000, v7
	s_waitcnt vmcnt(14)
	v_lshlrev_b32_e32 v50, 16, v8
	v_and_b32_e32 v51, 0xffff0000, v8
	v_lshlrev_b32_e32 v52, 16, v9
	v_and_b32_e32 v53, 0xffff0000, v9
	s_waitcnt vmcnt(13)
	v_lshlrev_b32_e32 v42, 16, v12
	v_and_b32_e32 v43, 0xffff0000, v12
	v_lshlrev_b32_e32 v44, 16, v13
	v_and_b32_e32 v45, 0xffff0000, v13
	s_waitcnt vmcnt(12)
	v_lshlrev_b32_e32 v22, 16, v14
	s_waitcnt vmcnt(11)
	v_lshlrev_b32_e32 v62, 16, v4
	v_and_b32_e32 v63, 0xffff0000, v4
	v_lshlrev_b32_e32 v64, 16, v5
	v_and_b32_e32 v65, 0xffff0000, v5
	s_waitcnt vmcnt(10)
	v_lshlrev_b32_e32 v54, 16, v10
	v_and_b32_e32 v55, 0xffff0000, v10
	v_lshlrev_b32_e32 v56, 16, v11
	v_and_b32_e32 v57, 0xffff0000, v11
	s_waitcnt vmcnt(9)
	v_lshlrev_b32_e32 v46, 16, v16
	v_and_b32_e32 v47, 0xffff0000, v16
	v_lshlrev_b32_e32 v48, 16, v17
	v_and_b32_e32 v49, 0xffff0000, v17
	s_waitcnt vmcnt(8)
	v_lshlrev_b32_e32 v26, 16, v18
	v_and_b32_e32 v27, 0xffff0000, v18
	v_lshlrev_b32_e32 v28, 16, v19
	v_and_b32_e32 v29, 0xffff0000, v19
	v_and_b32_e32 v23, 0xffff0000, v14
	v_lshlrev_b32_e32 v24, 16, v15
	v_and_b32_e32 v25, 0xffff0000, v15
	s_waitcnt vmcnt(7)
	v_lshlrev_b32_e32 v34, 16, v20
	v_and_b32_e32 v35, 0xffff0000, v20
	v_lshlrev_b32_e32 v36, 16, v21
	v_and_b32_e32 v37, 0xffff0000, v21
	s_waitcnt vmcnt(6)
	v_lshlrev_b32_e32 v38, 16, v30
	v_and_b32_e32 v39, 0xffff0000, v30
	v_lshlrev_b32_e32 v40, 16, v31
	v_and_b32_e32 v41, 0xffff0000, v31
	s_waitcnt vmcnt(5)
	v_lshlrev_b32_e32 v14, 16, v32
	v_and_b32_e32 v15, 0xffff0000, v32
	v_lshlrev_b32_e32 v16, 16, v33
	v_and_b32_e32 v17, 0xffff0000, v33
	s_waitcnt vmcnt(4)
	v_lshlrev_b32_e32 v30, 16, v106
	v_and_b32_e32 v31, 0xffff0000, v106
	v_lshlrev_b32_e32 v32, 16, v107
	v_and_b32_e32 v33, 0xffff0000, v107
	s_waitcnt vmcnt(3)
	v_lshlrev_b32_e32 v6, 16, v108
	v_and_b32_e32 v7, 0xffff0000, v108
	v_lshlrev_b32_e32 v8, 16, v109
	v_and_b32_e32 v9, 0xffff0000, v109
	s_waitcnt vmcnt(2)
	v_lshlrev_b32_e32 v18, 16, v110
	v_and_b32_e32 v19, 0xffff0000, v110
	v_lshlrev_b32_e32 v20, 16, v111
	v_and_b32_e32 v21, 0xffff0000, v111
	s_waitcnt lgkmcnt(0)
	s_waitcnt vmcnt(1)
	v_lshlrev_b32_e32 v2, 16, v112
	v_and_b32_e32 v3, 0xffff0000, v112
	v_lshlrev_b32_e32 v4, 16, v113
	v_and_b32_e32 v5, 0xffff0000, v113
	s_waitcnt vmcnt(0)
	v_lshlrev_b32_e32 v10, 16, v114
	v_and_b32_e32 v11, 0xffff0000, v114
	v_lshlrev_b32_e32 v12, 16, v115
	v_and_b32_e32 v13, 0xffff0000, v115
; __device__ __forceinline__ float bflo(unsigned w) { return __uint_as_float(w << 16); }
; __device__ __forceinline__ float bfhi(unsigned w) { return __uint_as_float(w & 0xffff0000u); }
; __device__ __forceinline__ void ln_phase(const Params& p, const int layer, const int row_lo, const int row_hi, const int wg_id, const int n_wg) {
;     ...
;             const f32x4* xr0 = (const f32x4*)((m0 < NP) ? p.in[0] + (size_t)m0 * DM : p.in[1] + (size_t)(m0 - NP) * DM) + lane;
;             const f32x4* xr1 = (const f32x4*)((m1 < NP) ? p.in[0] + (size_t)m1 * DM : p.in[1] + (size_t)(m1 - NP) * DM) + lane;
; #pragma unroll
;             for (int j = 0; j < 8; ++j) { v0[j] = xr0[64 * j]; v1[j] = xr1[64 * j]; w0[j] = ob0[64 * j]; w1[j] = ob1[64 * j]; }
;         } else {
;             const v2u* xb0 = (const v2u*)(XB + (size_t)m0 * DM) + lane; const v2u* xb1 = (const v2u*)(XB + (size_t)m1 * DM) + lane;
;             v2u a0[8], a1[8];
; #pragma unroll
;             for (int j = 0; j < 8; ++j) { a0[j] = xb0[64 * j]; a1[j] = xb1[64 * j]; w0[j] = ob0[64 * j]; w1[j] = ob1[64 * j]; }
; #pragma unroll
;             for (int j = 0; j < 8; ++j) { v0[j] = (f32x4){bflo(a0[j].x), bfhi(a0[j].x), bflo(a0[j].y), bfhi(a0[j].y)}; v1[j] = (f32x4){bflo(a1[j].x), bfhi(a1[j].x), bflo(a1[j].y), bfhi(a1[j].y)}; }
;         }
; #pragma unroll
;         for (int j = 0; j < 8; ++j) { v0[j] = v0[j] * DN_ALPHA + (f32x4){bflo(w0[j].x), bfhi(w0[j].x), bflo(w0[j].y), bfhi(w0[j].y)};
;             v1[j] = v1[j] * DN_ALPHA + (f32x4){bflo(w1[j].x), bfhi(w1[j].x), bflo(w1[j].y), bfhi(w1[j].y)};
;             s0 += (v0[j].x + v0[j].y) + (v0[j].z + v0[j].w); s1 += (v1[j].x + v1[j].y) + (v1[j].z + v1[j].w); }
.LBB0_1031:
	s_andn2_b64 vcc, exec, s[0:1]
	s_cbranch_vccnz .LBB0_1033
	v_add_u32_e32 v0, 0xffffe000, v66
	v_readlane_b32 s60, v251, 21
	v_lshlrev_b64 v[4:5], 13, v[0:1]
	v_readlane_b32 s62, v251, 23
	v_readlane_b32 s63, v251, 24
	s_movk_i32 s0, 0x2000
	v_add_u32_e32 v0, 0xffffe000, v104
	v_lshl_add_u64 v[2:3], s[46:47], 0, v[94:95]
	v_readlane_b32 s61, v251, 22
	v_lshl_add_u64 v[4:5], s[62:63], 0, v[4:5]
	v_cmp_gt_i32_e32 vcc, s0, v66
	v_lshlrev_b64 v[6:7], 13, v[0:1]
	v_mov_b32_e32 v99, v1
	v_cndmask_b32_e32 v3, v5, v3, vcc
	v_cndmask_b32_e32 v2, v4, v2, vcc
	v_lshl_add_u64 v[4:5], v[102:103], 2, s[60:61]
	v_lshl_add_u64 v[6:7], s[62:63], 0, v[6:7]
	v_cmp_gt_i32_e32 vcc, s0, v104
	v_lshl_add_u64 v[2:3], v[2:3], 0, v[98:99]
	s_movk_i32 s0, 0x1000
	v_cndmask_b32_e32 v5, v7, v5, vcc
	v_cndmask_b32_e32 v4, v6, v4, vcc
	v_lshl_add_u64 v[4:5], v[4:5], 0, v[98:99]
	global_load_dwordx4 v[62:65], v[2:3], off nt
	global_load_dwordx4 v[54:57], v[2:3], off offset:1024 nt
	global_load_dwordx4 v[58:61], v[4:5], off nt
	global_load_dwordx4 v[50:53], v[4:5], off offset:1024 nt
	global_load_dwordx4 v[46:49], v[2:3], off offset:2048 nt
	s_waitcnt lgkmcnt(0)
	global_load_dwordx4 v[26:29], v[2:3], off offset:3072 nt
	global_load_dwordx4 v[42:45], v[4:5], off offset:2048 nt
	global_load_dwordx4 v[22:25], v[4:5], off offset:3072 nt
	v_add_co_u32_e32 v2, vcc, s0, v2
	v_readlane_b32 s72, v251, 33
	s_nop 0
	v_addc_co_u32_e32 v3, vcc, 0, v3, vcc
	v_add_co_u32_e32 v10, vcc, s0, v4
	v_readlane_b32 s73, v251, 34
	s_nop 0
	v_addc_co_u32_e32 v11, vcc, 0, v5, vcc
	global_load_dwordx4 v[34:37], v[2:3], off nt
	global_load_dwordx4 v[14:17], v[2:3], off offset:1024 nt
	global_load_dwordx4 v[38:41], v[10:11], off nt
	global_load_dwordx4 v[30:33], v[10:11], off offset:1024 nt
	global_load_dwordx4 v[6:9], v[2:3], off offset:2048 nt
	s_nop 0
	global_load_dwordx4 v[2:5], v[2:3], off offset:3072 nt
	s_nop 0
	global_load_dwordx4 v[18:21], v[10:11], off offset:2048 nt
	s_nop 0
	global_load_dwordx4 v[10:13], v[10:11], off offset:3072 nt
	v_readlane_b32 s72, v248, 24
	v_readlane_b32 s73, v248, 25
	v_readlane_b32 s64, v251, 25
	v_readlane_b32 s65, v251, 26
	v_readlane_b32 s66, v251, 27
	v_readlane_b32 s67, v251, 28
	v_readlane_b32 s68, v251, 29
	v_readlane_b32 s69, v251, 30
	v_readlane_b32 s70, v251, 31
	v_readlane_b32 s71, v251, 32
	v_readlane_b32 s74, v251, 35
	v_readlane_b32 s75, v251, 36
.LBB0_1033:
	v_lshlrev_b64 v[104:105], 1, v[102:103]
	v_lshl_add_u64 v[110:111], v[68:69], 0, v[104:105]
	global_load_dwordx2 v[118:119], v[96:97], off offset:3584 nt
	global_load_dwordx2 v[120:121], v[96:97], off offset:3072 nt
	global_load_dwordx2 v[122:123], v[96:97], off offset:2560 nt
	global_load_dwordx2 v[126:127], v[96:97], off offset:2048 nt
	global_load_dwordx2 v[130:131], v[96:97], off offset:1536 nt
	global_load_dwordx2 v[106:107], v[96:97], off offset:1024 nt
	global_load_dwordx2 v[138:139], v[96:97], off offset:512 nt
	global_load_dwordx2 v[112:113], v[96:97], off nt
	global_load_dwordx2 v[140:141], v[110:111], off nt
	global_load_dwordx2 v[148:149], v[110:111], off offset:512 nt
	global_load_dwordx2 v[108:109], v[110:111], off offset:1024 nt
	global_load_dwordx2 v[136:137], v[110:111], off offset:1536 nt
	global_load_dwordx2 v[134:135], v[110:111], off offset:2048 nt
	global_load_dwordx2 v[132:133], v[110:111], off offset:2560 nt
	global_load_dwordx2 v[128:129], v[110:111], off offset:3072 nt
	global_load_dwordx2 v[124:125], v[110:111], off offset:3584 nt
	s_mov_b32 s2, 0xf800000
	v_lshl_add_u64 v[102:103], v[102:103], 2, v[72:73]
	s_waitcnt lgkmcnt(0)
	s_waitcnt vmcnt(8)
	v_lshlrev_b32_e32 v110, 16, v112
	v_and_b32_e32 v111, 0xffff0000, v112
	v_lshlrev_b32_e32 v112, 16, v113
	v_and_b32_e32 v113, 0xffff0000, v113
	v_pk_fma_f32 v[114:115], v[64:65], s[4:5], v[112:113] op_sel_hi:[1,0,1]
	v_pk_fma_f32 v[116:117], v[62:63], s[4:5], v[110:111] op_sel_hi:[1,0,1]
	s_waitcnt vmcnt(7)
	v_lshlrev_b32_e32 v62, 16, v140
	v_and_b32_e32 v63, 0xffff0000, v140
	v_lshlrev_b32_e32 v64, 16, v141
	v_and_b32_e32 v65, 0xffff0000, v141
	v_pk_fma_f32 v[110:111], v[60:61], s[4:5], v[64:65] op_sel_hi:[1,0,1]
	v_pk_fma_f32 v[112:113], v[58:59], s[4:5], v[62:63] op_sel_hi:[1,0,1]
	v_lshlrev_b32_e32 v58, 16, v138
	v_and_b32_e32 v59, 0xffff0000, v138
	v_lshlrev_b32_e32 v60, 16, v139
	v_and_b32_e32 v61, 0xffff0000, v139
	v_pk_fma_f32 v[56:57], v[56:57], s[4:5], v[60:61] op_sel_hi:[1,0,1]
	v_pk_fma_f32 v[54:55], v[54:55], s[4:5], v[58:59] op_sel_hi:[1,0,1]
	s_waitcnt vmcnt(6)
	v_lshlrev_b32_e32 v58, 16, v148
	v_and_b32_e32 v59, 0xffff0000, v148
	v_lshlrev_b32_e32 v60, 16, v149
	v_and_b32_e32 v61, 0xffff0000, v149
	v_pk_fma_f32 v[52:53], v[52:53], s[4:5], v[60:61] op_sel_hi:[1,0,1]
	v_pk_fma_f32 v[50:51], v[50:51], s[4:5], v[58:59] op_sel_hi:[1,0,1]
	v_mov_b32_e32 v58, v54
	v_mov_b32_e32 v59, v116
	v_mov_b32_e32 v60, v55
	v_mov_b32_e32 v61, v117
	v_pk_add_f32 v[58:59], v[58:59], v[60:61]
	v_mov_b32_e32 v60, v57
	v_mov_b32_e32 v61, v115
	v_mov_b32_e32 v62, v56
	v_mov_b32_e32 v63, v114
	v_pk_add_f32 v[60:61], v[60:61], v[62:63]
	v_mov_b32_e32 v62, v111
	v_pk_add_f32 v[58:59], v[58:59], v[60:61]
	v_mov_b32_e32 v60, v113
	v_add_f32_e32 v0, 0, v59
	v_add_f32_e32 v139, v58, v0
	v_mov_b32_e32 v58, v112
	v_mov_b32_e32 v59, v50
	v_mov_b32_e32 v61, v51
	v_pk_add_f32 v[58:59], v[58:59], v[60:61]
	v_mov_b32_e32 v60, v110
	v_mov_b32_e32 v61, v52
	v_mov_b32_e32 v63, v53
	v_pk_add_f32 v[60:61], v[60:61], v[62:63]
	s_nop 0
	v_pk_add_f32 v[58:59], v[58:59], v[60:61]
	v_lshlrev_b32_e32 v60, 16, v107
	v_add_f32_e32 v0, 0, v58
	v_add_f32_e32 v140, v0, v59
	v_lshlrev_b32_e32 v58, 16, v106
	v_and_b32_e32 v59, 0xffff0000, v106
	v_and_b32_e32 v61, 0xffff0000, v107
	v_pk_fma_f32 v[46:47], v[46:47], s[4:5], v[58:59] op_sel_hi:[1,0,1]
	v_pk_fma_f32 v[48:49], v[48:49], s[4:5], v[60:61] op_sel_hi:[1,0,1]
	s_waitcnt vmcnt(5)
; __device__ __forceinline__ float bflo(unsigned w) { return __uint_as_float(w << 16); }
; __device__ __forceinline__ float bfhi(unsigned w) { return __uint_as_float(w & 0xffff0000u); }
; __device__ __forceinline__ void ln_phase(const Params& p, const int layer, const int row_lo, const int row_hi, const int wg_id, const int n_wg) {
;     ...
;         for (int j = 0; j < 8; ++j) { v0[j] = v0[j] * DN_ALPHA + (f32x4){bflo(w0[j].x), bfhi(w0[j].x), bflo(w0[j].y), bfhi(w0[j].y)};
;             v1[j] = v1[j] * DN_ALPHA + (f32x4){bflo(w1[j].x), bfhi(w1[j].x), bflo(w1[j].y), bfhi(w1[j].y)};
;             s0 += (v0[j].x + v0[j].y) + (v0[j].z + v0[j].w); s1 += (v1[j].x + v1[j].y) + (v1[j].z + v1[j].w); }
;         const float mean0 = wave_sum(s0) * (1.f / DM), mean1 = wave_sum(s1) * (1.f / DM); float q0 = 0.f, q1 = 0.f;
	v_lshlrev_b32_e32 v58, 16, v108
	v_and_b32_e32 v59, 0xffff0000, v108
	v_lshlrev_b32_e32 v60, 16, v109
	v_and_b32_e32 v61, 0xffff0000, v109
	v_pk_fma_f32 v[108:109], v[44:45], s[4:5], v[60:61] op_sel_hi:[1,0,1]
	v_pk_fma_f32 v[106:107], v[42:43], s[4:5], v[58:59] op_sel_hi:[1,0,1]
	v_mov_b32_e32 v42, v46
	v_mov_b32_e32 v43, v49
	v_pk_mov_b32 v[44:45], v[46:47], v[48:49] op_sel:[1,0]
	s_nop 0
	v_pk_add_f32 v[42:43], v[42:43], v[44:45]
	v_mov_b32_e32 v44, v106
	v_pk_add_f32 v[148:149], v[42:43], v[42:43] op_sel_hi:[0,1]
	v_pk_mov_b32 v[42:43], v[106:107], v[108:109] op_sel:[1,0]
	v_mov_b32_e32 v45, v109
	v_pk_add_f32 v[42:43], v[42:43], v[44:45]
	v_lshlrev_b32_e32 v44, 16, v131
	v_pk_add_f32 v[150:151], v[42:43], v[42:43] op_sel:[0,1] op_sel_hi:[1,0]
	v_lshlrev_b32_e32 v42, 16, v130
	v_and_b32_e32 v43, 0xffff0000, v130
	v_and_b32_e32 v45, 0xffff0000, v131
	v_pk_fma_f32 v[64:65], v[28:29], s[4:5], v[44:45] op_sel_hi:[1,0,1]
	v_pk_fma_f32 v[62:63], v[26:27], s[4:5], v[42:43] op_sel_hi:[1,0,1]
	v_lshlrev_b32_e32 v42, 16, v126
	v_and_b32_e32 v43, 0xffff0000, v126
	v_lshlrev_b32_e32 v44, 16, v127
	v_and_b32_e32 v45, 0xffff0000, v127
	s_waitcnt vmcnt(4)
	v_lshlrev_b32_e32 v26, 16, v136
	v_and_b32_e32 v27, 0xffff0000, v136
	v_lshlrev_b32_e32 v28, 16, v137
	v_and_b32_e32 v29, 0xffff0000, v137
	v_pk_fma_f32 v[44:45], v[36:37], s[4:5], v[44:45] op_sel_hi:[1,0,1]
	v_pk_fma_f32 v[42:43], v[34:35], s[4:5], v[42:43] op_sel_hi:[1,0,1]
	v_pk_fma_f32 v[60:61], v[24:25], s[4:5], v[28:29] op_sel_hi:[1,0,1]
	v_pk_fma_f32 v[58:59], v[22:23], s[4:5], v[26:27] op_sel_hi:[1,0,1]
	v_add_f32_e32 v23, v62, v63
	v_add_f32_e32 v25, v65, v64
	s_waitcnt vmcnt(3)
	v_lshlrev_b32_e32 v34, 16, v134
	v_and_b32_e32 v35, 0xffff0000, v134
	v_lshlrev_b32_e32 v36, 16, v135
	v_and_b32_e32 v37, 0xffff0000, v135
	v_mov_b32_e32 v22, v42
	v_mov_b32_e32 v24, v43
	v_mov_b32_e32 v148, v45
	v_mov_b32_e32 v138, v44
	v_pk_fma_f32 v[40:41], v[40:41], s[4:5], v[36:37] op_sel_hi:[1,0,1]
	v_pk_fma_f32 v[38:39], v[38:39], s[4:5], v[34:35] op_sel_hi:[1,0,1]
	v_pk_add_f32 v[22:23], v[22:23], v[24:25]
	v_pk_add_f32 v[24:25], v[148:149], v[138:139]
	v_add_f32_e32 v26, v58, v59
	v_add_f32_e32 v28, v60, v61
	v_pk_add_f32 v[22:23], v[22:23], v[24:25]
	v_mov_b32_e32 v141, v38
	v_mov_b32_e32 v151, v39
	v_mov_b32_e32 v27, v40
	v_mov_b32_e32 v29, v41
	v_pk_add_f32 v[126:127], v[22:23], v[22:23] op_sel_hi:[0,1]
	v_pk_add_f32 v[22:23], v[140:141], v[150:151]
	v_pk_add_f32 v[24:25], v[26:27], v[28:29]
	s_nop 0
	v_pk_add_f32 v[22:23], v[22:23], v[24:25]
	v_lshlrev_b32_e32 v24, 16, v123
	v_pk_add_f32 v[130:131], v[22:23], v[22:23] op_sel:[0,1] op_sel_hi:[1,0]
	v_lshlrev_b32_e32 v22, 16, v122
	v_and_b32_e32 v23, 0xffff0000, v122
	v_and_b32_e32 v25, 0xffff0000, v123
	v_pk_fma_f32 v[34:35], v[14:15], s[4:5], v[22:23] op_sel_hi:[1,0,1]
	v_pk_fma_f32 v[36:37], v[16:17], s[4:5], v[24:25] op_sel_hi:[1,0,1]
	s_waitcnt vmcnt(2)
	v_lshlrev_b32_e32 v14, 16, v132
	v_and_b32_e32 v15, 0xffff0000, v132
	v_lshlrev_b32_e32 v16, 16, v133
	v_and_b32_e32 v17, 0xffff0000, v133
	v_pk_fma_f32 v[32:33], v[32:33], s[4:5], v[16:17] op_sel_hi:[1,0,1]
	v_pk_fma_f32 v[30:31], v[30:31], s[4:5], v[14:15] op_sel_hi:[1,0,1]
	v_mov_b32_e32 v14, v34
	v_mov_b32_e32 v15, v37
	v_pk_mov_b32 v[16:17], v[34:35], v[36:37] op_sel:[1,0]
	s_nop 0
	v_pk_add_f32 v[14:15], v[14:15], v[16:17]
	v_mov_b32_e32 v16, v30
	v_pk_add_f32 v[122:123], v[14:15], v[14:15] op_sel_hi:[0,1]
	v_pk_mov_b32 v[14:15], v[30:31], v[32:33] op_sel:[1,0]
	v_mov_b32_e32 v17, v33
	v_pk_add_f32 v[14:15], v[14:15], v[16:17]
	v_lshlrev_b32_e32 v16, 16, v121
	v_pk_add_f32 v[132:133], v[14:15], v[14:15] op_sel:[0,1] op_sel_hi:[1,0]
	v_lshlrev_b32_e32 v14, 16, v120
	v_and_b32_e32 v15, 0xffff0000, v120
	v_and_b32_e32 v17, 0xffff0000, v121
	v_pk_fma_f32 v[28:29], v[8:9], s[4:5], v[16:17] op_sel_hi:[1,0,1]
	v_pk_fma_f32 v[26:27], v[6:7], s[4:5], v[14:15] op_sel_hi:[1,0,1]
	s_waitcnt vmcnt(1)
	v_lshlrev_b32_e32 v8, 16, v129
	v_and_b32_e32 v9, 0xffff0000, v129
	v_lshlrev_b32_e32 v16, 16, v118
	v_and_b32_e32 v17, 0xffff0000, v118
	v_lshlrev_b32_e32 v14, 16, v119
	v_and_b32_e32 v15, 0xffff0000, v119
	v_lshlrev_b32_e32 v6, 16, v128
	v_and_b32_e32 v7, 0xffff0000, v128
	v_pk_fma_f32 v[24:25], v[20:21], s[4:5], v[8:9] op_sel_hi:[1,0,1]
	v_pk_fma_f32 v[14:15], v[4:5], s[4:5], v[14:15] op_sel_hi:[1,0,1]
	v_pk_fma_f32 v[20:21], v[2:3], s[4:5], v[16:17] op_sel_hi:[1,0,1]
	v_pk_fma_f32 v[22:23], v[18:19], s[4:5], v[6:7] op_sel_hi:[1,0,1]
	v_add_f32_e32 v7, v26, v27
	v_add_f32_e32 v9, v29, v28
	s_waitcnt vmcnt(0)
	v_lshlrev_b32_e32 v2, 16, v124
	v_and_b32_e32 v3, 0xffff0000, v124
	v_lshlrev_b32_e32 v4, 16, v125
	v_and_b32_e32 v5, 0xffff0000, v125
	v_mov_b32_e32 v6, v20
	v_mov_b32_e32 v8, v21
	v_mov_b32_e32 v122, v15
	v_mov_b32_e32 v126, v14
	v_pk_fma_f32 v[16:17], v[12:13], s[4:5], v[4:5] op_sel_hi:[1,0,1]
	v_pk_fma_f32 v[18:19], v[10:11], s[4:5], v[2:3] op_sel_hi:[1,0,1]
	v_pk_add_f32 v[2:3], v[6:7], v[8:9]
	v_pk_add_f32 v[4:5], v[122:123], v[126:127]
	v_add_f32_e32 v120, v22, v23
	v_add_f32_e32 v128, v24, v25
	v_pk_add_f32 v[2:3], v[2:3], v[4:5]
	v_mov_b32_e32 v131, v18
	v_mov_b32_e32 v133, v19
	v_mov_b32_e32 v121, v16
	v_mov_b32_e32 v129, v17
	v_add_f32_e32 v0, v2, v3
	v_pk_add_f32 v[2:3], v[130:131], v[132:133]
	v_pk_add_f32 v[4:5], v[120:121], v[128:129]
	s_nop 0
	v_pk_add_f32 v[2:3], v[2:3], v[4:5]
	s_nop 0
	v_add_f32_e32 v2, v2, v3
	ds_bpermute_b32 v3, v142, v0
	s_waitcnt lgkmcnt(0)
	v_add_f32_e32 v0, v0, v3
	ds_bpermute_b32 v3, v143, v0
	s_waitcnt lgkmcnt(0)
	v_add_f32_e32 v0, v0, v3
	ds_bpermute_b32 v3, v144, v0
	s_waitcnt lgkmcnt(0)
	v_add_f32_e32 v0, v0, v3
	ds_bpermute_b32 v3, v145, v0
	s_waitcnt lgkmcnt(0)
; __device__ __forceinline__ void ln_phase(const Params& p, const int layer, const int row_lo, const int row_hi, const int wg_id, const int n_wg) {
;     ...
;         const float mean0 = wave_sum(s0) * (1.f / DM), mean1 = wave_sum(s1) * (1.f / DM); float q0 = 0.f, q1 = 0.f;
; #pragma unroll
;         for (int j = 0; j < 8; ++j) { v0[j] = v0[j] - mean0; v1[j] = v1[j] - mean1;
;             q0 += (v0[j].x * v0[j].x + v0[j].y * v0[j].y) + (v0[j].z * v0[j].z + v0[j].w * v0[j].w); q1 += (v1[j].x * v1[j].x + v1[j].y * v1[j].y) + (v1[j].z * v1[j].z + v1[j].w * v1[j].w); }
;         const float rstd0 = 1.f / sqrtf(wave_sum(q0) * (1.f / DM) + LN_EPS), rstd1 = 1.f / sqrtf(wave_sum(q1) * (1.f / DM) + LN_EPS);
	v_add_f32_e32 v0, v0, v3
	ds_bpermute_b32 v3, v146, v0
	s_waitcnt lgkmcnt(0)
	v_add_f32_e32 v0, v0, v3
	ds_bpermute_b32 v3, v147, v0
	s_waitcnt lgkmcnt(0)
	v_add_f32_e32 v67, v0, v3
	ds_bpermute_b32 v0, v142, v2
	v_fmamk_f32 v117, v67, 0xba000000, v117
	v_fmac_f32_e32 v116, 0xba000000, v67
	v_fmamk_f32 v119, v67, 0xba000000, v55
	v_fmac_f32_e32 v54, 0xba000000, v67
	s_waitcnt lgkmcnt(0)
	v_add_f32_e32 v0, v2, v0
	ds_bpermute_b32 v2, v143, v0
	v_mov_b32_e32 v118, v117
	v_fmac_f32_e32 v114, 0xba000000, v67
	v_fmac_f32_e32 v56, 0xba000000, v67
	v_mov_b32_e32 v3, v54
	s_waitcnt lgkmcnt(0)
	v_add_f32_e32 v0, v0, v2
	ds_bpermute_b32 v2, v144, v0
	v_pk_mul_f32 v[4:5], v[118:119], v[118:119]
	v_fmamk_f32 v115, v67, 0xba000000, v115
	v_fmamk_f32 v127, v67, 0xba000000, v57
	v_mov_b32_e32 v126, v115
	s_waitcnt lgkmcnt(0)
	v_add_f32_e32 v0, v0, v2
	ds_bpermute_b32 v2, v145, v0
	v_fmamk_f32 v49, v67, 0xba000000, v49
	v_fmac_f32_e32 v48, 0xba000000, v67
	v_fmamk_f32 v47, v67, 0xba000000, v47
	v_fmac_f32_e32 v46, 0xba000000, v67
	s_waitcnt lgkmcnt(0)
	v_add_f32_e32 v0, v0, v2
	ds_bpermute_b32 v2, v146, v0
	v_fmac_f32_e32 v62, 0xba000000, v67
	v_fmac_f32_e32 v64, 0xba000000, v67
	v_fmamk_f32 v63, v67, 0xba000000, v63
	v_fmamk_f32 v65, v67, 0xba000000, v65
	s_waitcnt lgkmcnt(0)
	v_add_f32_e32 v0, v0, v2
	ds_bpermute_b32 v2, v147, v0
	v_fmamk_f32 v45, v67, 0xba000000, v45
	v_fmac_f32_e32 v44, 0xba000000, v67
	v_fmamk_f32 v43, v67, 0xba000000, v43
	v_fmac_f32_e32 v42, 0xba000000, v67
	s_waitcnt lgkmcnt(0)
	v_add_f32_e32 v99, v0, v2
	v_mov_b32_e32 v2, v116
	v_pk_fma_f32 v[2:3], v[2:3], v[2:3], v[4:5]
	v_mov_b32_e32 v4, v114
	v_mov_b32_e32 v5, v56
	v_fmamk_f32 v113, v99, 0xba000000, v113
	v_pk_mul_f32 v[4:5], v[4:5], v[4:5]
	v_fmamk_f32 v111, v99, 0xba000000, v111
	v_fmac_f32_e32 v112, 0xba000000, v99
	v_fmamk_f32 v123, v99, 0xba000000, v51
	v_fmac_f32_e32 v50, 0xba000000, v99
	v_pk_fma_f32 v[4:5], v[126:127], v[126:127], v[4:5]
	v_mov_b32_e32 v122, v113
	v_fmac_f32_e32 v110, 0xba000000, v99
	v_fmamk_f32 v125, v99, 0xba000000, v53
	v_fmac_f32_e32 v52, 0xba000000, v99
	v_pk_add_f32 v[2:3], v[2:3], v[4:5]
	v_mov_b32_e32 v4, v112
	v_mov_b32_e32 v5, v50
	v_pk_mul_f32 v[6:7], v[122:123], v[122:123]
	v_mov_b32_e32 v124, v111
	v_pk_fma_f32 v[4:5], v[4:5], v[4:5], v[6:7]
	v_mov_b32_e32 v6, v110
	v_mov_b32_e32 v7, v52
	v_pk_mul_f32 v[8:9], v[124:125], v[124:125]
	v_fmamk_f32 v109, v99, 0xba000000, v109
	v_pk_fma_f32 v[6:7], v[6:7], v[6:7], v[8:9]
	v_pk_mul_f32 v[8:9], v[46:47], v[46:47]
	v_pk_add_f32 v[4:5], v[4:5], v[6:7]
	v_pk_mul_f32 v[6:7], v[48:49], v[48:49]
	v_fmac_f32_e32 v108, 0xba000000, v99
	v_fmamk_f32 v107, v99, 0xba000000, v107
	v_fmac_f32_e32 v106, 0xba000000, v99
	v_pk_mov_b32 v[10:11], v[8:9], v[6:7] op_sel:[1,0]
	v_mov_b32_e32 v9, v7
	v_pk_add_f32 v[6:7], v[8:9], v[10:11]
	v_pk_mul_f32 v[8:9], v[108:109], v[108:109]
	v_pk_mul_f32 v[10:11], v[106:107], v[106:107]
	v_mul_f32_e32 v0, v62, v62
	v_pk_mov_b32 v[12:13], v[10:11], v[8:9] op_sel:[1,0]
	v_mov_b32_e32 v11, v9
	v_pk_add_f32 v[8:9], v[12:13], v[10:11]
	v_fmac_f32_e32 v58, 0xba000000, v99
	v_pk_fma_f32 v[10:11], v[62:63], v[62:63], v[0:1] op_sel_hi:[1,1,0]
	v_mul_f32_e32 v0, v64, v64
	v_fmac_f32_e32 v60, 0xba000000, v99
	v_fmamk_f32 v59, v99, 0xba000000, v59
	v_pk_fma_f32 v[12:13], v[64:65], v[64:65], v[0:1] op_sel_hi:[1,1,0]
	v_mul_f32_e32 v0, v58, v58
	v_fmamk_f32 v61, v99, 0xba000000, v61
	v_pk_fma_f32 v[120:121], v[58:59], v[58:59], v[0:1] op_sel_hi:[1,1,0]
	v_mul_f32_e32 v0, v60, v60
	v_pk_add_f32 v[2:3], v[2:3], v[2:3] op_sel_hi:[0,1]
	v_pk_add_f32 v[4:5], v[4:5], v[4:5] op_sel_hi:[0,1]
	v_pk_add_f32 v[6:7], v[6:7], v[6:7] op_sel_hi:[0,1]
	v_pk_add_f32 v[8:9], v[8:9], v[8:9] op_sel_hi:[0,1]
	v_pk_fma_f32 v[128:129], v[60:61], v[60:61], v[0:1] op_sel_hi:[1,1,0]
	v_fmamk_f32 v41, v99, 0xba000000, v41
	v_fmac_f32_e32 v40, 0xba000000, v99
	v_fmamk_f32 v39, v99, 0xba000000, v39
	v_fmac_f32_e32 v38, 0xba000000, v99
	v_mul_f32_e32 v2, v44, v44
	v_mul_f32_e32 v6, v45, v45
	v_mul_f32_e32 v120, v38, v38
	v_mul_f32_e32 v128, v39, v39
	v_mul_f32_e32 v8, v40, v40
	v_mul_f32_e32 v4, v41, v41
	v_mul_f32_e32 v10, v42, v42
	v_mul_f32_e32 v12, v43, v43
	v_pk_add_f32 v[2:3], v[6:7], v[2:3]
	v_pk_add_f32 v[6:7], v[120:121], v[128:129]
	v_pk_add_f32 v[4:5], v[8:9], v[4:5]
	v_fmamk_f32 v37, v67, 0xba000000, v37
	v_fmac_f32_e32 v36, 0xba000000, v67
	v_fmamk_f32 v35, v67, 0xba000000, v35
	v_fmac_f32_e32 v34, 0xba000000, v67
	v_pk_add_f32 v[10:11], v[10:11], v[12:13]
	v_pk_add_f32 v[4:5], v[6:7], v[4:5]
	v_pk_mul_f32 v[6:7], v[36:37], v[36:37]
	v_pk_mul_f32 v[8:9], v[34:35], v[34:35]
	v_pk_add_f32 v[2:3], v[10:11], v[2:3]
	v_fmamk_f32 v33, v99, 0xba000000, v33
	v_fmac_f32_e32 v32, 0xba000000, v99
	v_fmamk_f32 v31, v99, 0xba000000, v31
	v_fmac_f32_e32 v30, 0xba000000, v99
	v_pk_mov_b32 v[10:11], v[8:9], v[6:7] op_sel:[1,0]
	v_mov_b32_e32 v9, v7
	v_pk_add_f32 v[6:7], v[8:9], v[10:11]
	v_pk_mul_f32 v[8:9], v[32:33], v[32:33]
	v_pk_mul_f32 v[10:11], v[30:31], v[30:31]
	v_fmac_f32_e32 v26, 0xba000000, v67
	v_pk_mov_b32 v[12:13], v[10:11], v[8:9] op_sel:[1,0]
	v_mov_b32_e32 v11, v9
	v_fmac_f32_e32 v28, 0xba000000, v67
	v_fmamk_f32 v27, v67, 0xba000000, v27
	v_mul_f32_e32 v0, v26, v26
	v_pk_add_f32 v[8:9], v[12:13], v[10:11]
	v_fmamk_f32 v29, v67, 0xba000000, v29
	v_fmac_f32_e32 v22, 0xba000000, v99
	v_pk_fma_f32 v[10:11], v[26:27], v[26:27], v[0:1] op_sel_hi:[1,1,0]
	v_mul_f32_e32 v0, v28, v28
	v_pk_add_f32 v[2:3], v[2:3], v[2:3] op_sel_hi:[0,1]
	v_pk_add_f32 v[6:7], v[6:7], v[6:7] op_sel_hi:[0,1]
	v_fmac_f32_e32 v24, 0xba000000, v99
	v_fmamk_f32 v23, v99, 0xba000000, v23
	v_pk_fma_f32 v[12:13], v[28:29], v[28:29], v[0:1] op_sel_hi:[1,1,0]
	v_mul_f32_e32 v0, v22, v22
	v_fmamk_f32 v15, v67, 0xba000000, v15
	v_fmac_f32_e32 v14, 0xba000000, v67
	v_fmamk_f32 v21, v67, 0xba000000, v21
	v_fmac_f32_e32 v20, 0xba000000, v67
	v_fmamk_f32 v25, v99, 0xba000000, v25
	v_pk_fma_f32 v[120:121], v[22:23], v[22:23], v[0:1] op_sel_hi:[1,1,0]
	v_mul_f32_e32 v0, v24, v24
	v_mul_f32_e32 v10, v20, v20
	v_mul_f32_e32 v12, v21, v21
	v_mul_f32_e32 v2, v14, v14
	v_mul_f32_e32 v6, v15, v15
	v_pk_add_f32 v[4:5], v[4:5], v[4:5] op_sel_hi:[0,1]
	v_pk_add_f32 v[8:9], v[8:9], v[8:9] op_sel_hi:[0,1]
	v_pk_fma_f32 v[128:129], v[24:25], v[24:25], v[0:1] op_sel_hi:[1,1,0]
	v_fmamk_f32 v17, v99, 0xba000000, v17
	v_fmac_f32_e32 v16, 0xba000000, v99
	v_fmamk_f32 v19, v99, 0xba000000, v19
	v_fmac_f32_e32 v18, 0xba000000, v99
	v_pk_add_f32 v[10:11], v[10:11], v[12:13]
	v_pk_add_f32 v[2:3], v[6:7], v[2:3]
	v_mul_f32_e32 v120, v18, v18
	v_pk_add_f32 v[2:3], v[10:11], v[2:3]
	v_mul_f32_e32 v128, v19, v19
	v_mul_f32_e32 v8, v16, v16
	v_mul_f32_e32 v4, v17, v17
	v_add_f32_e32 v0, v2, v3
	v_pk_add_f32 v[2:3], v[120:121], v[128:129]
	v_pk_add_f32 v[4:5], v[8:9], v[4:5]
	v_lshl_add_u64 v[120:121], v[100:101], 0, v[94:95]
	v_pk_add_f32 v[2:3], v[2:3], v[4:5]
	s_nop 0
	v_add_f32_e32 v2, v2, v3
	ds_bpermute_b32 v3, v142, v0
	s_waitcnt lgkmcnt(0)
; __device__ __forceinline__ unsigned pk2(float lo, float hi) { return f2bf(lo) | (f2bf(hi) << 16); }
; __device__ __forceinline__ void ln_phase(const Params& p, const int layer, const int row_lo, const int row_hi, const int wg_id, const int n_wg) {
;     ...
;         const float rstd0 = 1.f / sqrtf(wave_sum(q0) * (1.f / DM) + LN_EPS), rstd1 = 1.f / sqrtf(wave_sum(q1) * (1.f / DM) + LN_EPS);
;         f32x4* zr0 = (f32x4*)(Z + (size_t)m0 * DM) + lane; f32x4* zr1 = (f32x4*)(Z + (size_t)m1 * DM) + lane;
;         unsigned long long* o80 = (unsigned long long*)(XB + (size_t)m0 * DM) + lane; unsigned long long* o81 = (unsigned long long*)(XB + (size_t)m1 * DM) + lane;
; #pragma unroll
;         for (int j = 0; j < 8; ++j) { const f32x4 gv = *((const f32x4*)g + lane + 64 * j), bv = *((const f32x4*)bb + lane + 64 * j);
;             const f32x4 y0 = v0[j] * rstd0 * gv + bv, y1 = v1[j] * rstd1 * gv + bv;
;             if (layer == 0) { o80[64 * j] = (unsigned long long)pk2(y0.x, y0.y) | ((unsigned long long)pk2(y0.z, y0.w) << 32);
;                 if (ok1) o81[64 * j] = (unsigned long long)pk2(y1.x, y1.y) | ((unsigned long long)pk2(y1.z, y1.w) << 32); }
;             else { zr0[64 * j] = y0; if (ok1) zr1[64 * j] = y1; } }
	v_add_f32_e32 v0, v0, v3
	ds_bpermute_b32 v3, v143, v0
	s_waitcnt lgkmcnt(0)
	v_add_f32_e32 v0, v0, v3
	ds_bpermute_b32 v3, v144, v0
	s_waitcnt lgkmcnt(0)
	v_add_f32_e32 v0, v0, v3
	ds_bpermute_b32 v3, v145, v0
	s_waitcnt lgkmcnt(0)
	v_add_f32_e32 v0, v0, v3
	ds_bpermute_b32 v3, v146, v0
	s_waitcnt lgkmcnt(0)
	v_add_f32_e32 v0, v0, v3
	ds_bpermute_b32 v3, v147, v0
	s_waitcnt lgkmcnt(0)
	v_add_f32_e32 v0, v0, v3
	v_fmamk_f32 v0, v0, 0x3a000000, v218
	v_cmp_gt_f32_e32 vcc, s2, v0
	v_mul_f32_e32 v3, 0x4f800000, v0
	s_nop 0
	v_cndmask_b32_e32 v0, v0, v3, vcc
	v_sqrt_f32_e32 v3, v0
	s_nop 0
	v_add_u32_e32 v4, -1, v3
	v_fma_f32 v5, -v4, v3, v0
	v_cmp_ge_f32_e64 s[0:1], 0, v5
	v_add_u32_e32 v5, 1, v3
	s_nop 0
	v_cndmask_b32_e64 v4, v3, v4, s[0:1]
	v_fma_f32 v3, -v5, v3, v0
	v_cmp_lt_f32_e64 s[0:1], 0, v3
	s_nop 1
	v_cndmask_b32_e64 v3, v4, v5, s[0:1]
	v_mul_f32_e32 v4, 0x37800000, v3
	v_cndmask_b32_e32 v3, v3, v4, vcc
	v_cmp_class_f32_e32 vcc, v0, v219
	s_nop 1
	v_cndmask_b32_e32 v0, v3, v0, vcc
	v_div_scale_f32 v3, s[0:1], v0, v0, 1.0
	v_rcp_f32_e32 v4, v3
	s_nop 0
	v_fma_f32 v5, -v3, v4, 1.0
	v_fmac_f32_e32 v4, v5, v4
	v_div_scale_f32 v5, vcc, 1.0, v0, 1.0
	v_mul_f32_e32 v6, v5, v4
	v_fma_f32 v7, -v3, v6, v5
	v_fmac_f32_e32 v6, v7, v4
	v_fma_f32 v3, -v3, v6, v5
	v_div_fmas_f32 v3, v3, v4, v6
	v_div_fixup_f32 v118, v3, v0, 1.0
	ds_bpermute_b32 v0, v142, v2
	v_pk_mul_f32 v[10:11], v[116:117], v[118:119] op_sel_hi:[1,0]
	v_pk_mul_f32 v[12:13], v[114:115], v[118:119] op_sel_hi:[1,0]
	s_waitcnt lgkmcnt(0)
	v_add_f32_e32 v0, v2, v0
	ds_bpermute_b32 v2, v143, v0
	s_waitcnt lgkmcnt(0)
	v_add_f32_e32 v0, v0, v2
	ds_bpermute_b32 v2, v144, v0
	s_waitcnt lgkmcnt(0)
	v_add_f32_e32 v0, v0, v2
	ds_bpermute_b32 v2, v145, v0
	s_waitcnt lgkmcnt(0)
	v_add_f32_e32 v0, v0, v2
	ds_bpermute_b32 v2, v146, v0
	s_waitcnt lgkmcnt(0)
	v_add_f32_e32 v0, v0, v2
	ds_bpermute_b32 v2, v147, v0
	s_waitcnt lgkmcnt(0)
	v_add_f32_e32 v0, v0, v2
	v_fmamk_f32 v0, v0, 0x3a000000, v218
	v_cmp_gt_f32_e32 vcc, s2, v0
	v_mul_f32_e32 v2, 0x4f800000, v0
	s_nop 0
	v_cndmask_b32_e32 v0, v0, v2, vcc
	v_sqrt_f32_e32 v2, v0
	s_nop 0
	v_add_u32_e32 v3, -1, v2
	v_fma_f32 v4, -v3, v2, v0
	v_cmp_ge_f32_e64 s[0:1], 0, v4
	v_add_u32_e32 v4, 1, v2
	s_nop 0
	v_cndmask_b32_e64 v3, v2, v3, s[0:1]
	v_fma_f32 v2, -v4, v2, v0
	v_cmp_lt_f32_e64 s[0:1], 0, v2
	s_nop 1
	v_cndmask_b32_e64 v2, v3, v4, s[0:1]
	v_mul_f32_e32 v3, 0x37800000, v2
	v_cndmask_b32_e32 v2, v2, v3, vcc
	v_cmp_class_f32_e32 vcc, v0, v219
	s_nop 1
	v_cndmask_b32_e32 v0, v2, v0, vcc
	v_div_scale_f32 v2, s[0:1], v0, v0, 1.0
	v_rcp_f32_e32 v3, v2
	s_mov_b64 s[0:1], -1
	v_fma_f32 v4, -v2, v3, 1.0
	v_fmac_f32_e32 v3, v4, v3
	v_div_scale_f32 v4, vcc, 1.0, v0, 1.0
	v_mul_f32_e32 v5, v4, v3
	v_fma_f32 v6, -v2, v5, v4
	v_fmac_f32_e32 v5, v6, v3
	v_fma_f32 v2, -v2, v5, v4
	v_div_fmas_f32 v2, v2, v3, v5
	v_div_fixup_f32 v122, v2, v0, 1.0
	v_mov_b64_e32 v[2:3], v[152:153]
	v_mov_b64_e32 v[4:5], v[154:155]
	v_mov_b64_e32 v[6:7], v[156:157]
	v_mov_b64_e32 v[8:9], v[158:159]
	v_pk_mul_f32 v[112:113], v[112:113], v[122:123] op_sel_hi:[1,0]
	v_pk_mul_f32 v[110:111], v[110:111], v[122:123] op_sel_hi:[1,0]
	s_and_b64 vcc, exec, s[10:11]
	v_pk_fma_f32 v[12:13], v[4:5], v[12:13], v[8:9]
	v_pk_fma_f32 v[10:11], v[2:3], v[10:11], v[6:7]
	v_pk_fma_f32 v[4:5], v[4:5], v[110:111], v[8:9]
	v_pk_fma_f32 v[2:3], v[2:3], v[112:113], v[6:7]
	s_cbranch_vccz .LBB0_1037
	global_store_dwordx4 v[120:121], v[10:13], off
	s_and_saveexec_b64 s[0:1], s[38:39]
	s_cbranch_execz .LBB0_1036
	global_store_dwordx4 v[102:103], v[2:5], off
